# bf16 rounding bit-trick sequences in the S5 carry/scan loops replaced by v_cvt_pk_bf16_f32 (same round-to-nearest-even)
# speedup vs baseline: 1.0025x; 1.0014x over previous
.LBB0_1008:
	v_bfe_u32 v87, v55, 4, 1
	v_and_b32_e32 v63, 15, v55
	v_lshlrev_b32_e32 v88, 4, v87
	v_or3_b32 v4, v88, s4, v63
	v_lshl_or_b32 v2, v4, 6, v59
	v_lshlrev_b32_e32 v228, 1, v2
	v_lshl_add_u64 v[0:1], v[228:229], 2, v[50:51]
	v_lshlrev_b32_e32 v228, 4, v2
	v_and_b32_e32 v68, 0xffffffe0, v55
	global_load_dwordx2 v[70:71], v[0:1], off
	v_lshlrev_b64 v[0:1], 2, v[228:229]
	v_ashrrev_i32_e32 v69, 31, v68
	v_lshl_add_u64 v[2:3], v[46:47], 0, v[0:1]
	v_lshl_add_u64 v[0:1], v[48:49], 0, v[0:1]
	v_lshl_or_b32 v228, v4, 12, v85
	v_lshlrev_b64 v[72:73], 13, v[68:69]
	global_load_dwordx4 v[32:35], v[2:3], off offset:48
	global_load_dwordx4 v[36:39], v[2:3], off offset:32
	global_load_dwordx4 v[40:43], v[2:3], off offset:16
	global_load_dwordx4 v[90:93], v[2:3], off
	global_load_dwordx4 v[12:15], v[0:1], off offset:48
	global_load_dwordx4 v[16:19], v[0:1], off offset:32
	global_load_dwordx4 v[20:23], v[0:1], off offset:16
	global_load_dwordx4 v[24:27], v[0:1], off
	v_lshl_add_u64 v[0:1], v[52:53], 0, v[228:229]
	v_lshl_add_u64 v[72:73], v[44:45], 0, v[72:73]
	v_lshlrev_b32_e32 v228, 6, v63
	v_lshlrev_b32_e32 v66, 4, v63
	v_lshl_add_u64 v[72:73], v[72:73], 0, v[228:229]
	v_mov_b32_e32 v63, v229
	v_lshl_add_u64 v[72:73], v[72:73], 0, v[62:63]
	v_mov_b32_e32 v65, v229
	global_load_dwordx4 v[28:31], v[0:1], off
	global_load_dwordx4 v[8:11], v[0:1], off offset:64
	global_load_dwordx4 v[4:7], v[0:1], off offset:128
	s_nop 0
	global_load_dwordx4 v[0:3], v[0:1], off offset:192
	v_lshl_add_u64 v[76:77], v[72:73], 0, v[64:65]
	global_load_dwordx4 v[72:75], v[76:77], off offset:16
	s_nop 0
	global_load_dwordx4 v[76:79], v[76:77], off
	s_mov_b32 s5, 0
	v_cmp_eq_u32_e32 vcc, 0, v87
	s_mov_b32 s6, 28
	s_waitcnt vmcnt(0)
	ds_write_b128 v84, v[76:79]
	ds_write_b128 v84, v[72:75] offset:16
	v_and_b32_e32 v208, 31, v59
	v_sub_u32_e32 v209, 31, v208
	v_mov_b32_e32 v217, 0x110
	v_mov_b32_e32 v210, 0xfffffef0
	v_cndmask_b32_e32 v208, v209, v208, vcc
	v_lshrrev_b32_e32 v209, 5, v59
	v_add_u32_e32 v211, 0x20f0, v54
	v_cndmask_b32_e32 v217, v210, v217, vcc
	v_lshlrev_b32_e32 v209, 2, v209
	v_cndmask_b32_e32 v216, v211, v54, vcc
	v_lshl_add_u32 v218, v208, 6, v67
	v_add_u32_e32 v218, v218, v209
	ds_read_b32 v200, v218
	ds_read_b32 v201, v218 offset:8
	ds_read_b32 v202, v218 offset:16
	ds_read_b32 v203, v218 offset:24
	ds_read_b32 v204, v218 offset:32
	ds_read_b32 v205, v218 offset:40
	ds_read_b32 v206, v218 offset:48
	ds_read_b32 v207, v218 offset:56
	v_permlane32_swap_b32_e32 v90, v91
	v_permlane32_swap_b32_e32 v92, v93
	v_permlane32_swap_b32_e32 v40, v41
	v_permlane32_swap_b32_e32 v42, v43
	v_permlane32_swap_b32_e32 v36, v37
	v_permlane32_swap_b32_e32 v38, v39
	v_permlane32_swap_b32_e32 v32, v33
	v_permlane32_swap_b32_e32 v34, v35
	v_permlane32_swap_b32_e32 v24, v25
	v_permlane32_swap_b32_e32 v26, v27
	v_permlane32_swap_b32_e32 v20, v21
	v_permlane32_swap_b32_e32 v22, v23
	v_permlane32_swap_b32_e32 v16, v17
	v_permlane32_swap_b32_e32 v18, v19
	v_permlane32_swap_b32_e32 v12, v13
	v_permlane32_swap_b32_e32 v14, v15
	s_waitcnt lgkmcnt(0)
	s_nop 1
	v_mfma_f32_32x32x2_f32 v[136:151], v200, v90, 0
	v_mfma_f32_32x32x2_f32 v[136:151], v201, v92, v[136:151]
	v_mfma_f32_32x32x2_f32 v[136:151], v202, v40, v[136:151]
	v_mfma_f32_32x32x2_f32 v[136:151], v203, v42, v[136:151]
	v_mfma_f32_32x32x2_f32 v[136:151], v204, v36, v[136:151]
	v_mfma_f32_32x32x2_f32 v[136:151], v205, v38, v[136:151]
	v_mfma_f32_32x32x2_f32 v[136:151], v206, v32, v[136:151]
	v_mfma_f32_32x32x2_f32 v[136:151], v207, v34, v[136:151]
	v_mfma_f32_32x32x2_f32 v[152:167], v200, v91, 0
	v_mfma_f32_32x32x2_f32 v[152:167], v201, v93, v[152:167]
	v_mfma_f32_32x32x2_f32 v[152:167], v202, v41, v[152:167]
	v_mfma_f32_32x32x2_f32 v[152:167], v203, v43, v[152:167]
	v_mfma_f32_32x32x2_f32 v[152:167], v204, v37, v[152:167]
	v_mfma_f32_32x32x2_f32 v[152:167], v205, v39, v[152:167]
	v_mfma_f32_32x32x2_f32 v[152:167], v206, v33, v[152:167]
	v_mfma_f32_32x32x2_f32 v[152:167], v207, v35, v[152:167]
	v_mfma_f32_32x32x2_f32 v[168:183], v200, v24, 0
	v_mfma_f32_32x32x2_f32 v[168:183], v201, v26, v[168:183]
	v_mfma_f32_32x32x2_f32 v[168:183], v202, v20, v[168:183]
	v_mfma_f32_32x32x2_f32 v[168:183], v203, v22, v[168:183]
	v_mfma_f32_32x32x2_f32 v[168:183], v204, v16, v[168:183]
	v_mfma_f32_32x32x2_f32 v[168:183], v205, v18, v[168:183]
	v_mfma_f32_32x32x2_f32 v[168:183], v206, v12, v[168:183]
	v_mfma_f32_32x32x2_f32 v[168:183], v207, v14, v[168:183]
	v_mfma_f32_32x32x2_f32 v[184:199], v200, v25, 0
	v_mfma_f32_32x32x2_f32 v[184:199], v201, v27, v[184:199]
	v_mfma_f32_32x32x2_f32 v[184:199], v202, v21, v[184:199]
	v_mfma_f32_32x32x2_f32 v[184:199], v203, v23, v[184:199]
	v_mfma_f32_32x32x2_f32 v[184:199], v204, v17, v[184:199]
	v_mfma_f32_32x32x2_f32 v[184:199], v205, v19, v[184:199]
	v_mfma_f32_32x32x2_f32 v[184:199], v206, v13, v[184:199]
	v_mfma_f32_32x32x2_f32 v[184:199], v207, v15, v[184:199]
	s_nop 15
	s_nop 3
	v_permlane32_swap_b32_e32 v136, v152
	v_permlane32_swap_b32_e32 v137, v153
	v_permlane32_swap_b32_e32 v138, v154
	v_permlane32_swap_b32_e32 v139, v155
	v_permlane32_swap_b32_e32 v140, v156
	v_permlane32_swap_b32_e32 v141, v157
	v_permlane32_swap_b32_e32 v142, v158
	v_permlane32_swap_b32_e32 v143, v159
	v_permlane32_swap_b32_e32 v144, v160
	v_permlane32_swap_b32_e32 v145, v161
	v_permlane32_swap_b32_e32 v146, v162
	v_permlane32_swap_b32_e32 v147, v163
	v_permlane32_swap_b32_e32 v148, v164
	v_permlane32_swap_b32_e32 v149, v165
	v_permlane32_swap_b32_e32 v150, v166
	v_permlane32_swap_b32_e32 v151, v167
	v_permlane32_swap_b32_e32 v168, v184
	v_permlane32_swap_b32_e32 v169, v185
	v_permlane32_swap_b32_e32 v170, v186
	v_permlane32_swap_b32_e32 v171, v187
	v_permlane32_swap_b32_e32 v172, v188
	v_permlane32_swap_b32_e32 v173, v189
	v_permlane32_swap_b32_e32 v174, v190
	v_permlane32_swap_b32_e32 v175, v191
	v_permlane32_swap_b32_e32 v176, v192
	v_permlane32_swap_b32_e32 v177, v193
	v_permlane32_swap_b32_e32 v178, v194
	v_permlane32_swap_b32_e32 v179, v195
	v_permlane32_swap_b32_e32 v180, v196
	v_permlane32_swap_b32_e32 v181, v197
	v_permlane32_swap_b32_e32 v182, v198
	v_permlane32_swap_b32_e32 v183, v199
	v_mov_b32_e32 v32, 0
	v_mov_b32_e32 v33, 0
	v_mul_f32_e32 v208, v71, v33
	v_mul_f32_e32 v209, v71, v32
	v_fma_f32 v32, v70, v32, -v208
	v_fma_f32 v33, v70, v33, v209
	v_add_f32_e32 v32, v32, v136
	v_add_f32_e32 v33, v33, v168
	v_cvt_pk_bf16_f32 v210, v32, v33
	ds_write_b32 v216, v210 offset:2048
	v_add_u32_e32 v216, v216, v217
	v_mul_f32_e32 v208, v71, v33
	v_mul_f32_e32 v209, v71, v32
	v_fma_f32 v32, v70, v32, -v208
	v_fma_f32 v33, v70, v33, v209
	v_add_f32_e32 v32, v32, v137
	v_add_f32_e32 v33, v33, v169
	v_cvt_pk_bf16_f32 v210, v32, v33
	ds_write_b32 v216, v210 offset:2048
	v_add_u32_e32 v216, v216, v217
	v_mul_f32_e32 v208, v71, v33
	v_mul_f32_e32 v209, v71, v32
	v_fma_f32 v32, v70, v32, -v208
	v_fma_f32 v33, v70, v33, v209
	v_add_f32_e32 v32, v32, v138
	v_add_f32_e32 v33, v33, v170
	v_cvt_pk_bf16_f32 v210, v32, v33
	ds_write_b32 v216, v210 offset:2048
	v_add_u32_e32 v216, v216, v217
	v_mul_f32_e32 v208, v71, v33
	v_mul_f32_e32 v209, v71, v32
	v_fma_f32 v32, v70, v32, -v208
	v_fma_f32 v33, v70, v33, v209
	v_add_f32_e32 v32, v32, v139
	v_add_f32_e32 v33, v33, v171
	v_cvt_pk_bf16_f32 v210, v32, v33
	ds_write_b32 v216, v210 offset:2048
	v_add_u32_e32 v216, v216, v217
	v_mul_f32_e32 v208, v71, v33
	v_mul_f32_e32 v209, v71, v32
	v_fma_f32 v32, v70, v32, -v208
	v_fma_f32 v33, v70, v33, v209
	v_add_f32_e32 v32, v32, v152
	v_add_f32_e32 v33, v33, v184
	v_cvt_pk_bf16_f32 v210, v32, v33
	ds_write_b32 v216, v210 offset:2048
	v_add_u32_e32 v216, v216, v217
	v_mul_f32_e32 v208, v71, v33
	v_mul_f32_e32 v209, v71, v32
	v_fma_f32 v32, v70, v32, -v208
	v_fma_f32 v33, v70, v33, v209
	v_add_f32_e32 v32, v32, v153
	v_add_f32_e32 v33, v33, v185
	v_cvt_pk_bf16_f32 v210, v32, v33
	ds_write_b32 v216, v210 offset:2048
	v_add_u32_e32 v216, v216, v217
	v_mul_f32_e32 v208, v71, v33
	v_mul_f32_e32 v209, v71, v32
	v_fma_f32 v32, v70, v32, -v208
	v_fma_f32 v33, v70, v33, v209
	v_add_f32_e32 v32, v32, v154
	v_add_f32_e32 v33, v33, v186
	v_cvt_pk_bf16_f32 v210, v32, v33
	ds_write_b32 v216, v210 offset:2048
	v_add_u32_e32 v216, v216, v217
	v_mul_f32_e32 v208, v71, v33
	v_mul_f32_e32 v209, v71, v32
	v_fma_f32 v32, v70, v32, -v208
	v_fma_f32 v33, v70, v33, v209
	v_add_f32_e32 v32, v32, v155
	v_add_f32_e32 v33, v33, v187
	v_cvt_pk_bf16_f32 v210, v32, v33
	ds_write_b32 v216, v210 offset:2048
	v_add_u32_e32 v216, v216, v217
	v_mul_f32_e32 v208, v71, v33
	v_mul_f32_e32 v209, v71, v32
	v_fma_f32 v32, v70, v32, -v208
	v_fma_f32 v33, v70, v33, v209
	v_add_f32_e32 v32, v32, v140
	v_add_f32_e32 v33, v33, v172
	v_cvt_pk_bf16_f32 v210, v32, v33
	ds_write_b32 v216, v210 offset:2048
	v_add_u32_e32 v216, v216, v217
	v_mul_f32_e32 v208, v71, v33
	v_mul_f32_e32 v209, v71, v32
	v_fma_f32 v32, v70, v32, -v208
	v_fma_f32 v33, v70, v33, v209
	v_add_f32_e32 v32, v32, v141
	v_add_f32_e32 v33, v33, v173
	v_cvt_pk_bf16_f32 v210, v32, v33
	ds_write_b32 v216, v210 offset:2048
	v_add_u32_e32 v216, v216, v217
	v_mul_f32_e32 v208, v71, v33
	v_mul_f32_e32 v209, v71, v32
	v_fma_f32 v32, v70, v32, -v208
	v_fma_f32 v33, v70, v33, v209
	v_add_f32_e32 v32, v32, v142
	v_add_f32_e32 v33, v33, v174
	v_cvt_pk_bf16_f32 v210, v32, v33
	ds_write_b32 v216, v210 offset:2048
	v_add_u32_e32 v216, v216, v217
	v_mul_f32_e32 v208, v71, v33
	v_mul_f32_e32 v209, v71, v32
	v_fma_f32 v32, v70, v32, -v208
	v_fma_f32 v33, v70, v33, v209
	v_add_f32_e32 v32, v32, v143
	v_add_f32_e32 v33, v33, v175
	v_cvt_pk_bf16_f32 v210, v32, v33
	ds_write_b32 v216, v210 offset:2048
	v_add_u32_e32 v216, v216, v217
	v_mul_f32_e32 v208, v71, v33
	v_mul_f32_e32 v209, v71, v32
	v_fma_f32 v32, v70, v32, -v208
	v_fma_f32 v33, v70, v33, v209
	v_add_f32_e32 v32, v32, v156
	v_add_f32_e32 v33, v33, v188
	v_cvt_pk_bf16_f32 v210, v32, v33
	ds_write_b32 v216, v210 offset:2048
	v_add_u32_e32 v216, v216, v217
	v_mul_f32_e32 v208, v71, v33
	v_mul_f32_e32 v209, v71, v32
	v_fma_f32 v32, v70, v32, -v208
	v_fma_f32 v33, v70, v33, v209
	v_add_f32_e32 v32, v32, v157
	v_add_f32_e32 v33, v33, v189
	v_cvt_pk_bf16_f32 v210, v32, v33
	ds_write_b32 v216, v210 offset:2048
	v_add_u32_e32 v216, v216, v217
	v_mul_f32_e32 v208, v71, v33
	v_mul_f32_e32 v209, v71, v32
	v_fma_f32 v32, v70, v32, -v208
	v_fma_f32 v33, v70, v33, v209
	v_add_f32_e32 v32, v32, v158
	v_add_f32_e32 v33, v33, v190
	v_cvt_pk_bf16_f32 v210, v32, v33
	ds_write_b32 v216, v210 offset:2048
	v_add_u32_e32 v216, v216, v217
	v_mul_f32_e32 v208, v71, v33
	v_mul_f32_e32 v209, v71, v32
	v_fma_f32 v32, v70, v32, -v208
	v_fma_f32 v33, v70, v33, v209
	v_add_f32_e32 v32, v32, v159
	v_add_f32_e32 v33, v33, v191
	v_cvt_pk_bf16_f32 v210, v32, v33
	ds_write_b32 v216, v210 offset:2048
	v_add_u32_e32 v216, v216, v217
	v_mul_f32_e32 v208, v71, v33
	v_mul_f32_e32 v209, v71, v32
	v_fma_f32 v32, v70, v32, -v208
	v_fma_f32 v33, v70, v33, v209
	v_add_f32_e32 v32, v32, v144
	v_add_f32_e32 v33, v33, v176
	v_cvt_pk_bf16_f32 v210, v32, v33
	ds_write_b32 v216, v210 offset:2048
	v_add_u32_e32 v216, v216, v217
	v_mul_f32_e32 v208, v71, v33
	v_mul_f32_e32 v209, v71, v32
	v_fma_f32 v32, v70, v32, -v208
	v_fma_f32 v33, v70, v33, v209
	v_add_f32_e32 v32, v32, v145
	v_add_f32_e32 v33, v33, v177
	v_cvt_pk_bf16_f32 v210, v32, v33
	ds_write_b32 v216, v210 offset:2048
	v_add_u32_e32 v216, v216, v217
	v_mul_f32_e32 v208, v71, v33
	v_mul_f32_e32 v209, v71, v32
	v_fma_f32 v32, v70, v32, -v208
	v_fma_f32 v33, v70, v33, v209
	v_add_f32_e32 v32, v32, v146
	v_add_f32_e32 v33, v33, v178
	v_cvt_pk_bf16_f32 v210, v32, v33
	ds_write_b32 v216, v210 offset:2048
	v_add_u32_e32 v216, v216, v217
	v_mul_f32_e32 v208, v71, v33
	v_mul_f32_e32 v209, v71, v32
	v_fma_f32 v32, v70, v32, -v208
	v_fma_f32 v33, v70, v33, v209
	v_add_f32_e32 v32, v32, v147
	v_add_f32_e32 v33, v33, v179
	v_cvt_pk_bf16_f32 v210, v32, v33
	ds_write_b32 v216, v210 offset:2048
	v_add_u32_e32 v216, v216, v217
	v_mul_f32_e32 v208, v71, v33
	v_mul_f32_e32 v209, v71, v32
	v_fma_f32 v32, v70, v32, -v208
	v_fma_f32 v33, v70, v33, v209
	v_add_f32_e32 v32, v32, v160
	v_add_f32_e32 v33, v33, v192
	v_cvt_pk_bf16_f32 v210, v32, v33
	ds_write_b32 v216, v210 offset:2048
	v_add_u32_e32 v216, v216, v217
	v_mul_f32_e32 v208, v71, v33
	v_mul_f32_e32 v209, v71, v32
	v_fma_f32 v32, v70, v32, -v208
	v_fma_f32 v33, v70, v33, v209
	v_add_f32_e32 v32, v32, v161
	v_add_f32_e32 v33, v33, v193
	v_cvt_pk_bf16_f32 v210, v32, v33
	ds_write_b32 v216, v210 offset:2048
	v_add_u32_e32 v216, v216, v217
	v_mul_f32_e32 v208, v71, v33
	v_mul_f32_e32 v209, v71, v32
	v_fma_f32 v32, v70, v32, -v208
	v_fma_f32 v33, v70, v33, v209
	v_add_f32_e32 v32, v32, v162
	v_add_f32_e32 v33, v33, v194
	v_cvt_pk_bf16_f32 v210, v32, v33
	ds_write_b32 v216, v210 offset:2048
	v_add_u32_e32 v216, v216, v217
	v_mul_f32_e32 v208, v71, v33
	v_mul_f32_e32 v209, v71, v32
	v_fma_f32 v32, v70, v32, -v208
	v_fma_f32 v33, v70, v33, v209
	v_add_f32_e32 v32, v32, v163
	v_add_f32_e32 v33, v33, v195
	v_cvt_pk_bf16_f32 v210, v32, v33
	ds_write_b32 v216, v210 offset:2048
	v_add_u32_e32 v216, v216, v217
	v_mul_f32_e32 v208, v71, v33
	v_mul_f32_e32 v209, v71, v32
	v_fma_f32 v32, v70, v32, -v208
	v_fma_f32 v33, v70, v33, v209
	v_add_f32_e32 v32, v32, v148
	v_add_f32_e32 v33, v33, v180
	v_cvt_pk_bf16_f32 v210, v32, v33
	ds_write_b32 v216, v210 offset:2048
	v_add_u32_e32 v216, v216, v217
	v_mul_f32_e32 v208, v71, v33
	v_mul_f32_e32 v209, v71, v32
	v_fma_f32 v32, v70, v32, -v208
	v_fma_f32 v33, v70, v33, v209
	v_add_f32_e32 v32, v32, v149
	v_add_f32_e32 v33, v33, v181
	v_cvt_pk_bf16_f32 v210, v32, v33
	ds_write_b32 v216, v210 offset:2048
	v_add_u32_e32 v216, v216, v217
	v_mul_f32_e32 v208, v71, v33
	v_mul_f32_e32 v209, v71, v32
	v_fma_f32 v32, v70, v32, -v208
	v_fma_f32 v33, v70, v33, v209
	v_add_f32_e32 v32, v32, v150
	v_add_f32_e32 v33, v33, v182
	v_cvt_pk_bf16_f32 v210, v32, v33
	ds_write_b32 v216, v210 offset:2048
	v_add_u32_e32 v216, v216, v217
	v_mul_f32_e32 v208, v71, v33
	v_mul_f32_e32 v209, v71, v32
	v_fma_f32 v32, v70, v32, -v208
	v_fma_f32 v33, v70, v33, v209
	v_add_f32_e32 v32, v32, v151
	v_add_f32_e32 v33, v33, v183
	v_cvt_pk_bf16_f32 v210, v32, v33
	ds_write_b32 v216, v210 offset:2048
	v_add_u32_e32 v216, v216, v217
	v_mul_f32_e32 v208, v71, v33
	v_mul_f32_e32 v209, v71, v32
	v_fma_f32 v32, v70, v32, -v208
	v_fma_f32 v33, v70, v33, v209
	v_add_f32_e32 v32, v32, v164
	v_add_f32_e32 v33, v33, v196
	v_cvt_pk_bf16_f32 v210, v32, v33
	ds_write_b32 v216, v210 offset:2048
	v_add_u32_e32 v216, v216, v217
	v_mul_f32_e32 v208, v71, v33
	v_mul_f32_e32 v209, v71, v32
	v_fma_f32 v32, v70, v32, -v208
	v_fma_f32 v33, v70, v33, v209
	v_add_f32_e32 v32, v32, v165
	v_add_f32_e32 v33, v33, v197
	v_cvt_pk_bf16_f32 v210, v32, v33
	ds_write_b32 v216, v210 offset:2048
	v_add_u32_e32 v216, v216, v217
	v_mul_f32_e32 v208, v71, v33
	v_mul_f32_e32 v209, v71, v32
	v_fma_f32 v32, v70, v32, -v208
	v_fma_f32 v33, v70, v33, v209
	v_add_f32_e32 v32, v32, v166
	v_add_f32_e32 v33, v33, v198
	v_cvt_pk_bf16_f32 v210, v32, v33
	ds_write_b32 v216, v210 offset:2048
	v_add_u32_e32 v216, v216, v217
	v_mul_f32_e32 v208, v71, v33
	v_mul_f32_e32 v209, v71, v32
	v_fma_f32 v32, v70, v32, -v208
	v_fma_f32 v33, v70, v33, v209
	v_add_f32_e32 v32, v32, v167
	v_add_f32_e32 v33, v33, v199
	v_cvt_pk_bf16_f32 v210, v32, v33
	ds_write_b32 v216, v210 offset:2048
	s_movk_i32 s5, 0xffef
	v_and_or_b32 v12, v55, s5, v88
	v_ashrrev_i32_e32 v13, 31, v12
	v_lshlrev_b64 v[12:13], 9, v[12:13]
	v_lshl_add_u64 v[12:13], v[56:57], 0, v[12:13]
	global_store_dwordx2 v[12:13], v[32:33], off
	ds_read_b128 v[12:15], v86 offset:2048
	ds_read_b128 v[20:23], v86 offset:2112
	ds_read_b128 v[16:19], v86 offset:6400
	v_lshlrev_b32_e32 v228, 13, v87
	v_add_u32_e32 v55, s77, v55
	v_cmp_lt_i32_e32 vcc, s86, v55
	s_or_b64 s[2:3], vcc, s[2:3]
	s_waitcnt lgkmcnt(2)
	v_mfma_f32_16x16x32_bf16 v[12:15], v[12:15], v[28:31], 0
	s_waitcnt lgkmcnt(1)
	v_mfma_f32_16x16x32_bf16 v[12:15], v[20:23], v[8:11], v[12:15]
	ds_read_b128 v[20:23], v86 offset:6464
	s_waitcnt lgkmcnt(1)
	v_mfma_f32_16x16x32_bf16 v[16:19], v[16:19], v[28:31], 0
	s_waitcnt lgkmcnt(0)
	v_mfma_f32_16x16x32_bf16 v[8:11], v[20:23], v[8:11], v[16:19]
	s_nop 5
	ds_read_b128 v[16:19], v86 offset:2176
	s_waitcnt lgkmcnt(0)
	v_mfma_f32_16x16x32_bf16 v[12:15], v[16:19], v[4:7], v[12:15]
	ds_read_b128 v[16:19], v86 offset:6528
	s_waitcnt lgkmcnt(0)
	v_mfma_f32_16x16x32_bf16 v[4:7], v[16:19], v[4:7], v[8:11]
	s_nop 2
	ds_read_b128 v[8:11], v86 offset:2240
	s_waitcnt lgkmcnt(0)
	v_mfma_f32_16x16x32_bf16 v[8:11], v[8:11], v[0:3], v[12:15]
	s_nop 2
	ds_read_b128 v[12:15], v86 offset:6592
	s_waitcnt lgkmcnt(0)
	v_mfma_f32_16x16x32_bf16 v[0:3], v[12:15], v[0:3], v[4:7]
	s_nop 2
	v_lshl_add_u64 v[4:5], v[228:229], 0, v[68:69]
	v_or_b32_e32 v4, v4, v58
	v_lshlrev_b32_e32 v228, 2, v66
	v_lshl_add_u64 v[6:7], v[60:61], 0, v[228:229]
	v_lshlrev_b64 v[4:5], 10, v[4:5]
	v_lshl_add_u64 v[12:13], v[6:7], 0, v[4:5]
	global_store_dword v[12:13], v8, off
	global_store_dword v[12:13], v9, off offset:1024
	global_store_dword v[12:13], v10, off offset:2048
	global_store_dword v[12:13], v11, off offset:3072
	v_or_b32_e32 v8, 0x4000, v4
	v_mov_b32_e32 v9, v5
	v_lshl_add_u64 v[8:9], v[6:7], 0, v[8:9]
	global_store_dword v[8:9], v0, off
	v_or_b32_e32 v8, 0x4400, v4
	v_mov_b32_e32 v9, v5
	v_lshl_add_u64 v[8:9], v[6:7], 0, v[8:9]
	global_store_dword v[8:9], v1, off
	v_or_b32_e32 v0, 0x4800, v4
	v_mov_b32_e32 v1, v5
	v_lshl_add_u64 v[0:1], v[6:7], 0, v[0:1]
	v_or_b32_e32 v4, 0x4c00, v4
	global_store_dword v[0:1], v2, off
	v_lshl_add_u64 v[0:1], v[6:7], 0, v[4:5]
	global_store_dword v[0:1], v3, off
	s_andn2_b64 exec, exec, s[2:3]
	s_cbranch_execnz .LBB0_1008

.LBB0_1144:
	v_pk_mul_f32 v[22:23], v[20:21], v[22:23] op_sel_hi:[1,0]
	v_add_u32_e32 v28, s0, v65
	v_pk_fma_f32 v[26:27], v[16:17], v[18:19], v[22:23] op_sel_hi:[1,0,1]
	v_pk_fma_f32 v[18:19], v[16:17], v[18:19], v[22:23] op_sel_hi:[1,0,1] neg_lo:[0,0,1] neg_hi:[0,0,1]
	v_cvt_pk_bf16_f32 v25, v18, v27
	v_pk_mul_f32 v[22:23], v[20:21], v[26:27] op_sel:[0,1]
	s_addk_i32 s0, 0x880
	v_pk_fma_f32 v[26:27], v[16:17], v[18:19], v[22:23] op_sel_hi:[1,0,1]
	v_pk_fma_f32 v[18:19], v[16:17], v[18:19], v[22:23] op_sel_hi:[1,0,1] neg_lo:[0,0,1] neg_hi:[0,0,1]
	v_cvt_pk_bf16_f32 v22, v18, v27
	ds_write2_b32 v28, v25, v22 offset1:68
	v_pk_mul_f32 v[22:23], v[20:21], v[26:27] op_sel:[0,1]
	s_cmpk_eq_i32 s0, 0x2200
	v_pk_fma_f32 v[26:27], v[16:17], v[18:19], v[22:23] op_sel_hi:[1,0,1]
	v_pk_fma_f32 v[18:19], v[16:17], v[18:19], v[22:23] op_sel_hi:[1,0,1] neg_lo:[0,0,1] neg_hi:[0,0,1]
	v_cvt_pk_bf16_f32 v25, v18, v27
	v_pk_mul_f32 v[22:23], v[20:21], v[26:27] op_sel:[0,1]
	s_nop 0
	v_pk_fma_f32 v[26:27], v[16:17], v[18:19], v[22:23] op_sel_hi:[1,0,1]
	v_pk_fma_f32 v[18:19], v[16:17], v[18:19], v[22:23] op_sel_hi:[1,0,1] neg_lo:[0,0,1] neg_hi:[0,0,1]
	v_cvt_pk_bf16_f32 v22, v18, v27
	ds_write2_b32 v28, v25, v22 offset0:136 offset1:204
	v_pk_mul_f32 v[22:23], v[20:21], v[26:27] op_sel:[0,1]
	v_add_u32_e32 v28, 0x400, v28
	v_pk_fma_f32 v[26:27], v[16:17], v[18:19], v[22:23] op_sel_hi:[1,0,1]
	v_pk_fma_f32 v[18:19], v[16:17], v[18:19], v[22:23] op_sel_hi:[1,0,1] neg_lo:[0,0,1] neg_hi:[0,0,1]
	v_cvt_pk_bf16_f32 v25, v18, v27
	v_pk_mul_f32 v[22:23], v[20:21], v[26:27] op_sel:[0,1]
	s_nop 0
	v_pk_fma_f32 v[26:27], v[16:17], v[18:19], v[22:23] op_sel_hi:[1,0,1]
	v_pk_fma_f32 v[18:19], v[16:17], v[18:19], v[22:23] op_sel_hi:[1,0,1] neg_lo:[0,0,1] neg_hi:[0,0,1]
	v_cvt_pk_bf16_f32 v22, v18, v27
	ds_write2_b32 v28, v25, v22 offset0:16 offset1:84
	v_pk_mul_f32 v[22:23], v[20:21], v[26:27] op_sel:[0,1]
	s_nop 0
	v_pk_fma_f32 v[26:27], v[16:17], v[18:19], v[22:23] op_sel_hi:[1,0,1]
	v_pk_fma_f32 v[18:19], v[16:17], v[18:19], v[22:23] op_sel_hi:[1,0,1] neg_lo:[0,0,1] neg_hi:[0,0,1]
	v_bfe_u32 v23, v27, 16, 1
	v_bfe_u32 v22, v18, 16, 1
	v_add3_u32 v22, v18, v22, s89
	v_lshrrev_b32_e32 v22, 16, v22
	v_add3_u32 v23, v27, v23, s89
	v_pk_mul_f32 v[26:27], v[20:21], v[26:27] op_sel:[0,1]
	v_and_or_b32 v25, v23, s75, v22
	v_pk_fma_f32 v[22:23], v[16:17], v[18:19], v[26:27] op_sel_hi:[1,0,1]
	v_pk_fma_f32 v[18:19], v[16:17], v[18:19], v[26:27] op_sel_hi:[1,0,1] neg_lo:[0,0,1] neg_hi:[0,0,1]
	v_cvt_pk_bf16_f32 v19, v18, v23
	v_mov_b32_e32 v22, v23
	ds_write2_b32 v28, v25, v19 offset0:152 offset1:220
	s_cbranch_scc0 .LBB0_1144
	v_add3_u32 v16, v24, v139, s95
	v_ashrrev_i32_e32 v17, 31, v16
	v_lshlrev_b64 v[16:17], 8, v[16:17]
	v_lshl_add_u64 v[16:17], v[72:73], 0, v[16:17]
	global_load_dwordx4 v[28:31], v[16:17], off
	global_load_dwordx4 v[24:27], v[16:17], off offset:64
	global_load_dwordx4 v[20:23], v[16:17], off offset:128
	s_nop 0
	global_load_dwordx4 v[16:19], v[16:17], off offset:192
	v_lshl_add_u32 v170, v33, 1, v32
	v_mad_u32_u24 v32, v139, s22, v170
	ds_read_b128 v[60:63], v32
	ds_read_b128 v[56:59], v32 offset:64
	ds_read_b128 v[44:47], v32 offset:4352
	ds_read_b128 v[40:43], v32 offset:4416
	ds_read_b128 v[52:55], v32 offset:128
	ds_read_b128 v[48:51], v32 offset:192
	ds_read_b128 v[36:39], v32 offset:4480
	ds_read_b128 v[32:35], v32 offset:4544
	v_mul_u32_u24_e32 v171, 0x110, v139
	v_pk_mov_b32 v[132:133], v[128:129], v[128:129] op_sel:[1,0]
	s_movk_i32 s0, 0x1980
	v_mov_b32_e32 v134, v131
.LBB0_1146:
	v_pk_mul_f32 v[134:135], v[132:133], v[134:135] op_sel_hi:[1,0]
	v_add_u32_e32 v175, s0, v65
	v_pk_fma_f32 v[172:173], v[128:129], v[130:131], v[134:135] op_sel_hi:[1,0,1]
	v_pk_fma_f32 v[130:131], v[128:129], v[130:131], v[134:135] op_sel_hi:[1,0,1] neg_lo:[0,0,1] neg_hi:[0,0,1]
	v_cvt_pk_bf16_f32 v174, v130, v173
	v_pk_mul_f32 v[134:135], v[132:133], v[172:173] op_sel:[0,1]
	v_add_u32_e32 v176, 0x400, v175
	v_pk_fma_f32 v[172:173], v[128:129], v[130:131], v[134:135] op_sel_hi:[1,0,1]
	v_pk_fma_f32 v[130:131], v[128:129], v[130:131], v[134:135] op_sel_hi:[1,0,1] neg_lo:[0,0,1] neg_hi:[0,0,1]
	v_cvt_pk_bf16_f32 v134, v130, v173
	ds_write2_b32 v176, v134, v174 offset0:152 offset1:220
	v_pk_mul_f32 v[134:135], v[132:133], v[172:173] op_sel:[0,1]
	s_addk_i32 s0, 0xf780
	v_pk_fma_f32 v[172:173], v[128:129], v[130:131], v[134:135] op_sel_hi:[1,0,1]
	v_pk_fma_f32 v[130:131], v[128:129], v[130:131], v[134:135] op_sel_hi:[1,0,1] neg_lo:[0,0,1] neg_hi:[0,0,1]
	v_cvt_pk_bf16_f32 v174, v130, v173
	v_pk_mul_f32 v[134:135], v[132:133], v[172:173] op_sel:[0,1]
	s_cmpk_lg_i32 s0, 0xf780
	v_pk_fma_f32 v[172:173], v[128:129], v[130:131], v[134:135] op_sel_hi:[1,0,1]
	v_pk_fma_f32 v[130:131], v[128:129], v[130:131], v[134:135] op_sel_hi:[1,0,1] neg_lo:[0,0,1] neg_hi:[0,0,1]
	v_cvt_pk_bf16_f32 v134, v130, v173
	ds_write2_b32 v176, v134, v174 offset0:16 offset1:84
	v_pk_mul_f32 v[134:135], v[132:133], v[172:173] op_sel:[0,1]
	s_nop 0
	v_pk_fma_f32 v[172:173], v[128:129], v[130:131], v[134:135] op_sel_hi:[1,0,1]
	v_pk_fma_f32 v[130:131], v[128:129], v[130:131], v[134:135] op_sel_hi:[1,0,1] neg_lo:[0,0,1] neg_hi:[0,0,1]
	v_cvt_pk_bf16_f32 v174, v130, v173
	v_pk_mul_f32 v[134:135], v[132:133], v[172:173] op_sel:[0,1]
	s_nop 0
	v_pk_fma_f32 v[172:173], v[128:129], v[130:131], v[134:135] op_sel_hi:[1,0,1]
	v_pk_fma_f32 v[130:131], v[128:129], v[130:131], v[134:135] op_sel_hi:[1,0,1] neg_lo:[0,0,1] neg_hi:[0,0,1]
	v_cvt_pk_bf16_f32 v134, v130, v173
	ds_write2_b32 v175, v134, v174 offset0:136 offset1:204
	v_pk_mul_f32 v[134:135], v[132:133], v[172:173] op_sel:[0,1]
	s_nop 0
	v_pk_fma_f32 v[172:173], v[128:129], v[130:131], v[134:135] op_sel_hi:[1,0,1]
	v_pk_fma_f32 v[130:131], v[128:129], v[130:131], v[134:135] op_sel_hi:[1,0,1] neg_lo:[0,0,1] neg_hi:[0,0,1]
	v_bfe_u32 v135, v173, 16, 1
	v_bfe_u32 v134, v130, 16, 1
	v_add3_u32 v134, v130, v134, s89
	v_lshrrev_b32_e32 v134, 16, v134
	v_add3_u32 v135, v173, v135, s89
	v_pk_mul_f32 v[172:173], v[132:133], v[172:173] op_sel:[0,1]
	v_and_or_b32 v174, v135, s75, v134
	v_pk_fma_f32 v[134:135], v[128:129], v[130:131], v[172:173] op_sel_hi:[1,0,1]
	v_pk_fma_f32 v[130:131], v[128:129], v[130:131], v[172:173] op_sel_hi:[1,0,1] neg_lo:[0,0,1] neg_hi:[0,0,1]
	v_cvt_pk_bf16_f32 v131, v130, v135
	v_mov_b32_e32 v134, v135
	ds_write2_b32 v175, v131, v174 offset1:68
	s_cbranch_scc1 .LBB0_1146
	s_waitcnt lgkmcnt(11)
	v_mfma_f32_16x16x32_bf16 v[60:63], v[60:63], v[12:15], 0
	v_add_u32_e32 v131, v170, v171
	v_add_f32_e32 v128, v156, v157
	s_waitcnt lgkmcnt(10)
	v_mfma_f32_16x16x32_bf16 v[56:59], v[56:59], v[8:11], v[60:63]
	v_add_f32_e32 v129, v160, v161
	v_add_f32_e32 v160, v154, v155
	v_lshlrev_b32_e32 v130, 1, v139
	s_nop 0
	ds_read_b128 v[60:63], v131
	s_waitcnt lgkmcnt(8)
	v_mfma_f32_16x16x32_bf16 v[52:55], v[52:55], v[4:7], v[56:59]
	v_add_f32_e32 v158, v158, v159
	v_lshlrev_b32_e32 v159, 1, v64
	v_add_f32_e32 v172, v166, v167
	ds_read_b128 v[56:59], v131 offset:64
	v_mfma_f32_16x16x32_bf16 v[12:15], v[44:47], v[12:15], 0
	v_add_f32_e32 v171, v164, v165
	v_add_f32_e32 v170, v162, v163
	v_add_f32_e32 v169, v168, v169
	s_waitcnt lgkmcnt(8)
	v_mfma_f32_16x16x32_bf16 v[48:51], v[48:51], v[0:3], v[52:55]
	s_mov_b32 s0, 0
	s_nop 1
	ds_read_b128 v[52:55], v131 offset:128
	v_mfma_f32_16x16x32_bf16 v[8:11], v[40:43], v[8:11], v[12:15]
	s_waitcnt vmcnt(3) lgkmcnt(2)
	v_mfma_f32_16x16x32_bf16 v[48:51], v[60:63], v[28:31], v[48:51]
	ds_read_b128 v[60:63], v131 offset:192
	v_mfma_f32_16x16x32_bf16 v[4:7], v[36:39], v[4:7], v[8:11]
	s_waitcnt vmcnt(2) lgkmcnt(2)
	v_mfma_f32_16x16x32_bf16 v[48:51], v[56:59], v[24:27], v[48:51]
	ds_read_b128 v[56:59], v131 offset:4352
	ds_read_b128 v[132:135], v131 offset:4416
	v_mfma_f32_16x16x32_bf16 v[0:3], v[32:35], v[0:3], v[4:7]
	s_waitcnt vmcnt(1) lgkmcnt(3)
	v_mfma_f32_16x16x32_bf16 v[48:51], v[52:55], v[20:23], v[48:51]
	ds_read_b128 v[52:55], v131 offset:4480
	ds_read_b128 v[154:157], v131 offset:4544
	s_waitcnt lgkmcnt(3)
	v_mfma_f32_16x16x32_bf16 v[0:3], v[56:59], v[28:31], v[0:3]
	s_waitcnt vmcnt(0)
	v_mfma_f32_16x16x32_bf16 v[48:51], v[60:63], v[16:19], v[48:51]
	s_waitcnt lgkmcnt(2)
	v_mfma_f32_16x16x32_bf16 v[0:3], v[132:135], v[24:27], v[0:3]
	v_mul_u32_u24_e32 v132, 0x840, v149
	s_nop 4
	v_add_f32_e32 v48, v128, v48
	v_fmac_f32_e32 v48, v153, v148
	v_mul_f32_e32 v60, 0x3d372713, v48
	v_mul_f32_e32 v44, v48, v60
	v_add_f32_e32 v13, v160, v49
	s_waitcnt lgkmcnt(1)
	v_mfma_f32_16x16x32_bf16 v[0:3], v[52:55], v[20:23], v[0:3]
	v_fma_f32 v44, v48, v44, v48
	v_fmac_f32_e32 v13, v152, v148
	v_mul_f32_e32 v44, 0xbfcc422a, v44
	v_mul_f32_e32 v9, 0x3d372713, v13
	v_add_f32_e32 v21, v129, v50
	v_mul_f32_e32 v44, 0x3fb8aa3b, v44
	v_mul_f32_e32 v4, v13, v9
	v_fmac_f32_e32 v21, v151, v148
	v_exp_f32_e32 v12, v44
	v_fma_f32 v4, v13, v4, v13
	s_waitcnt lgkmcnt(0)
	v_mfma_f32_16x16x32_bf16 v[16:19], v[154:157], v[16:19], v[0:3]
	v_mul_f32_e32 v4, 0xbfcc422a, v4
	v_mul_f32_e32 v4, 0x3fb8aa3b, v4
	v_exp_f32_e32 v4, v4
	v_mul_f32_e32 v0, 0x3d372713, v21
	v_mul_f32_e32 v0, v21, v0
	v_fma_f32 v0, v21, v0, v21
	v_mul_f32_e32 v0, 0xbfcc422a, v0
	v_add_f32_e32 v8, 1.0, v12
	v_mul_f32_e32 v0, 0x3fb8aa3b, v0
	v_rcp_f32_e32 v8, v8
	v_exp_f32_e32 v0, v0
	v_add_f32_e32 v4, 1.0, v4
	v_rcp_f32_e32 v4, v4
	v_lshlrev_b32_e32 v128, 4, v143
	v_mul_f32_e32 v5, v48, v8
	v_add_f32_e32 v0, 1.0, v0
	v_ashrrev_i32_e32 v129, 31, v128
	v_bfe_u32 v6, v5, 16, 1
	v_rcp_f32_e32 v25, v0
	v_lshlrev_b64 v[0:1], 2, v[128:129]
	v_add3_u32 v5, v5, v6, s89
	v_add3_u32 v24, v130, v159, v132
	v_lshl_add_u64 v[2:3], v[76:77], 0, v[0:1]
	ds_write_b16_d16_hi v24, v5 offset:34816
	v_mul_f32_e32 v22, v13, v4
	v_lshl_add_u64 v[4:5], v[2:3], 0, v[80:81]
	v_lshl_add_u64 v[0:1], v[78:79], 0, v[0:1]
	v_add_co_u32_e32 v6, vcc, s92, v4
	v_add_f32_e32 v26, v158, v51
	s_nop 0
	v_addc_co_u32_e32 v7, vcc, 0, v5, vcc
	global_load_dword v157, v[4:5], off
	global_load_dword v158, v[6:7], off
	v_lshl_add_u64 v[4:5], v[0:1], 0, v[82:83]
	global_load_dword v151, v[4:5], off
	v_lshl_add_u64 v[4:5], v[2:3], 0, v[84:85]
	v_add_co_u32_e32 v6, vcc, s92, v4
	v_fmac_f32_e32 v26, v150, v148
	s_nop 0
	v_addc_co_u32_e32 v7, vcc, 0, v5, vcc
	global_load_dword v153, v[4:5], off
	global_load_dword v154, v[6:7], off
	v_lshl_add_u64 v[4:5], v[0:1], 0, v[86:87]
	global_load_dword v152, v[4:5], off
	v_lshl_add_u64 v[4:5], v[2:3], 0, v[88:89]
	v_add_co_u32_e32 v6, vcc, s92, v4
	v_add_u32_e32 v20, s5, v128
	s_nop 0
	v_addc_co_u32_e32 v7, vcc, 0, v5, vcc
	global_load_dword v159, v[4:5], off
	global_load_dword v160, v[6:7], off
	v_lshl_add_u64 v[4:5], v[0:1], 0, v[90:91]
	global_load_dword v150, v[4:5], off
	v_lshl_add_u64 v[4:5], v[2:3], 0, v[92:93]
	v_add_co_u32_e32 v6, vcc, s92, v4
	v_mul_f32_e32 v27, 0x3d372713, v26
	s_nop 0
	v_addc_co_u32_e32 v7, vcc, 0, v5, vcc
	global_load_dword v155, v[4:5], off
	global_load_dword v156, v[6:7], off
	v_lshl_add_u64 v[4:5], v[0:1], 0, v[94:95]
	global_load_dword v149, v[4:5], off
	v_lshl_add_u64 v[4:5], v[2:3], 0, v[96:97]
	v_add_co_u32_e32 v6, vcc, s92, v4
	v_mul_f32_e32 v27, v26, v27
	s_nop 0
	v_addc_co_u32_e32 v7, vcc, 0, v5, vcc
	global_load_dword v164, v[4:5], off
	global_load_dword v166, v[6:7], off
	v_lshl_add_u64 v[4:5], v[0:1], 0, v[98:99]
	global_load_dword v135, v[4:5], off
	v_lshl_add_u64 v[4:5], v[2:3], 0, v[100:101]
	v_add_co_u32_e32 v6, vcc, s92, v4
	v_fma_f32 v27, v26, v27, v26
	s_nop 0
	v_addc_co_u32_e32 v7, vcc, 0, v5, vcc
	global_load_dword v161, v[4:5], off
	global_load_dword v162, v[6:7], off
	v_lshl_add_u64 v[4:5], v[0:1], 0, v[102:103]
	global_load_dword v134, v[4:5], off
	v_lshl_add_u64 v[4:5], v[2:3], 0, v[104:105]
	v_add_co_u32_e32 v6, vcc, s92, v4
	v_lshl_add_u64 v[2:3], v[2:3], 0, v[110:111]
	s_nop 0
	v_addc_co_u32_e32 v7, vcc, 0, v5, vcc
	global_load_dword v167, v[4:5], off
	global_load_dword v168, v[6:7], off
	v_lshl_add_u64 v[4:5], v[0:1], 0, v[106:107]
	global_load_dword v129, v[4:5], off
	v_add_co_u32_e32 v4, vcc, s92, v2
	v_lshl_add_u64 v[0:1], v[0:1], 0, v[108:109]
	s_nop 0
	v_addc_co_u32_e32 v5, vcc, 0, v3, vcc
	global_load_dword v163, v[2:3], off
	global_load_dword v165, v[4:5], off
	ds_read_b64 v[2:3], v229 offset:63640
	global_load_dword v133, v[0:1], off
	v_add_u32_e32 v0, v128, v140
	v_ashrrev_i32_e32 v1, 31, v0
	v_mul_f32_e32 v27, 0xbfcc422a, v27
	s_waitcnt lgkmcnt(0)
	v_lshl_add_u64 v[0:1], v[0:1], 2, v[2:3]
	global_load_dword v143, v[0:1], off
	v_or_b32_e32 v0, v20, v139
	v_ashrrev_i32_e32 v1, 31, v0
	v_lshlrev_b64 v[0:1], 8, v[0:1]
	v_lshl_add_u64 v[0:1], v[72:73], 0, v[0:1]
	global_load_dwordx4 v[12:15], v[0:1], off
	global_load_dwordx4 v[8:11], v[0:1], off offset:64
	global_load_dwordx4 v[4:7], v[0:1], off offset:128
	s_nop 0
	global_load_dwordx4 v[0:3], v[0:1], off offset:192
	v_mul_f32_e32 v27, 0x3fb8aa3b, v27
	v_exp_f32_e32 v27, v27
	v_bfe_u32 v23, v22, 16, 1
	v_add3_u32 v22, v22, v23, s89
	ds_write_b16_d16_hi v24, v22 offset:35344
	v_add_f32_e32 v22, 1.0, v27
	v_rcp_f32_e32 v22, v22
	v_mul_f32_e32 v21, v21, v25
	v_bfe_u32 v23, v21, 16, 1
	v_add_f32_e32 v16, v172, v16
	v_add3_u32 v21, v21, v23, s89
	v_fmac_f32_e32 v16, v144, v148
	ds_write_b16_d16_hi v24, v21 offset:35872
	v_mul_f32_e32 v21, v26, v22
	v_mul_f32_e32 v22, 0x3d372713, v16
	v_mul_f32_e32 v22, v16, v22
	v_fma_f32 v22, v16, v22, v16
	v_mul_f32_e32 v22, 0xbfcc422a, v22
	v_mul_f32_e32 v22, 0x3fb8aa3b, v22
	v_exp_f32_e32 v22, v22
	v_bfe_u32 v23, v21, 16, 1
	v_add_f32_e32 v17, v170, v17
	v_add3_u32 v21, v21, v23, s89
	v_fmac_f32_e32 v17, v145, v148
	ds_write_b16_d16_hi v24, v21 offset:36400
	v_add_f32_e32 v21, 1.0, v22
	v_mul_f32_e32 v22, 0x3d372713, v17
	v_mul_f32_e32 v22, v17, v22
	v_fma_f32 v22, v17, v22, v17
	v_rcp_f32_e32 v21, v21
	v_mul_f32_e32 v22, 0xbfcc422a, v22
	v_mul_f32_e32 v22, 0x3fb8aa3b, v22
	v_exp_f32_e32 v22, v22
	v_mul_f32_e32 v16, v16, v21
	v_add_f32_e32 v18, v169, v18
	v_bfe_u32 v21, v16, 16, 1
	v_fmac_f32_e32 v18, v146, v148
	v_add3_u32 v16, v16, v21, s89
	v_add_f32_e32 v21, 1.0, v22
	v_mul_f32_e32 v22, 0x3d372713, v18
	v_mul_f32_e32 v22, v18, v22
	v_fma_f32 v22, v18, v22, v18
	v_mul_f32_e32 v22, 0xbfcc422a, v22
	v_mul_f32_e32 v22, 0x3fb8aa3b, v22
	v_rcp_f32_e32 v21, v21
	v_exp_f32_e32 v22, v22
	v_add_f32_e32 v19, v171, v19
	v_fmac_f32_e32 v19, v147, v148
	ds_write_b16_d16_hi v24, v16 offset:43264
	v_mul_f32_e32 v16, v17, v21
	v_add_f32_e32 v21, 1.0, v22
	v_mul_f32_e32 v22, 0x3d372713, v19
	v_mul_f32_e32 v22, v19, v22
	v_fma_f32 v22, v19, v22, v19
	v_mul_f32_e32 v22, 0xbfcc422a, v22
	v_mul_f32_e32 v22, 0x3fb8aa3b, v22
	v_exp_f32_e32 v22, v22
	v_rcp_f32_e32 v21, v21
	v_bfe_u32 v17, v16, 16, 1
	v_add3_u32 v16, v16, v17, s89
	v_add_f32_e32 v17, 1.0, v22
	v_rcp_f32_e32 v17, v17
	ds_write_b16_d16_hi v24, v16 offset:43792
	v_mul_f32_e32 v16, v18, v21
	v_bfe_u32 v18, v16, 16, 1
	v_add3_u32 v16, v16, v18, s89
	ds_write_b16_d16_hi v24, v16 offset:44320
	v_mul_f32_e32 v16, v19, v17
	v_bfe_u32 v17, v16, 16, 1
	v_add3_u32 v16, v16, v17, s89
	ds_write_b16_d16_hi v24, v16 offset:44848
	v_pk_mov_b32 v[16:17], v[124:125], v[124:125] op_sel:[1,0]
	v_mov_b32_e32 v18, v127
.LBB0_1148:
	v_pk_mul_f32 v[18:19], v[16:17], v[18:19] op_sel_hi:[1,0]
	v_add_u32_e32 v26, s0, v65
	v_pk_fma_f32 v[22:23], v[124:125], v[126:127], v[18:19] op_sel_hi:[1,0,1]
	v_pk_fma_f32 v[18:19], v[124:125], v[126:127], v[18:19] op_sel_hi:[1,0,1] neg_lo:[0,0,1] neg_hi:[0,0,1]
	v_bfe_u32 v24, v23, 16, 1
	v_bfe_u32 v21, v18, 16, 1
	v_add3_u32 v21, v18, v21, s89
	v_lshrrev_b32_e32 v21, 16, v21
	v_add3_u32 v24, v23, v24, s89
	v_pk_mul_f32 v[22:23], v[16:17], v[22:23] op_sel:[0,1]
	v_and_or_b32 v21, v24, s75, v21
	v_pk_fma_f32 v[24:25], v[124:125], v[18:19], v[22:23] op_sel_hi:[1,0,1]
	v_pk_fma_f32 v[18:19], v[124:125], v[18:19], v[22:23] op_sel_hi:[1,0,1] neg_lo:[0,0,1] neg_hi:[0,0,1]
	v_cvt_pk_bf16_f32 v22, v18, v25
	ds_write2_b32 v26, v21, v22 offset1:68
	v_pk_mul_f32 v[22:23], v[16:17], v[24:25] op_sel:[0,1]
	s_addk_i32 s0, 0x880
	v_pk_fma_f32 v[24:25], v[124:125], v[18:19], v[22:23] op_sel_hi:[1,0,1]
	v_pk_fma_f32 v[18:19], v[124:125], v[18:19], v[22:23] op_sel_hi:[1,0,1] neg_lo:[0,0,1] neg_hi:[0,0,1]
	v_cvt_pk_bf16_f32 v21, v18, v25
	v_pk_mul_f32 v[22:23], v[16:17], v[24:25] op_sel:[0,1]
	s_cmpk_lg_i32 s0, 0x2200
	v_pk_fma_f32 v[24:25], v[124:125], v[18:19], v[22:23] op_sel_hi:[1,0,1]
	v_pk_fma_f32 v[18:19], v[124:125], v[18:19], v[22:23] op_sel_hi:[1,0,1] neg_lo:[0,0,1] neg_hi:[0,0,1]
	v_cvt_pk_bf16_f32 v22, v18, v25
	ds_write2_b32 v26, v21, v22 offset0:136 offset1:204
	v_pk_mul_f32 v[22:23], v[16:17], v[24:25] op_sel:[0,1]
	v_add_u32_e32 v26, 0x400, v26
	v_pk_fma_f32 v[24:25], v[124:125], v[18:19], v[22:23] op_sel_hi:[1,0,1]
	v_pk_fma_f32 v[18:19], v[124:125], v[18:19], v[22:23] op_sel_hi:[1,0,1] neg_lo:[0,0,1] neg_hi:[0,0,1]
	v_cvt_pk_bf16_f32 v21, v18, v25
	v_pk_mul_f32 v[22:23], v[16:17], v[24:25] op_sel:[0,1]
	s_nop 0
	v_pk_fma_f32 v[24:25], v[124:125], v[18:19], v[22:23] op_sel_hi:[1,0,1]
	v_pk_fma_f32 v[18:19], v[124:125], v[18:19], v[22:23] op_sel_hi:[1,0,1] neg_lo:[0,0,1] neg_hi:[0,0,1]
	v_cvt_pk_bf16_f32 v22, v18, v25
	ds_write2_b32 v26, v21, v22 offset0:16 offset1:84
	v_pk_mul_f32 v[22:23], v[16:17], v[24:25] op_sel:[0,1]
	s_nop 0
	v_pk_fma_f32 v[24:25], v[124:125], v[18:19], v[22:23] op_sel_hi:[1,0,1]
	v_pk_fma_f32 v[22:23], v[124:125], v[18:19], v[22:23] op_sel_hi:[1,0,1] neg_lo:[0,0,1] neg_hi:[0,0,1]
	v_bfe_u32 v19, v25, 16, 1
	v_bfe_u32 v18, v22, 16, 1
	v_add3_u32 v18, v22, v18, s89
	v_lshrrev_b32_e32 v18, 16, v18
	v_add3_u32 v19, v25, v19, s89
	v_pk_mul_f32 v[24:25], v[16:17], v[24:25] op_sel:[0,1]
	v_and_or_b32 v21, v19, s75, v18
	v_pk_fma_f32 v[18:19], v[124:125], v[22:23], v[24:25] op_sel_hi:[1,0,1]
	v_pk_fma_f32 v[126:127], v[124:125], v[22:23], v[24:25] op_sel_hi:[1,0,1] neg_lo:[0,0,1] neg_hi:[0,0,1]
	v_cvt_pk_bf16_f32 v18, v126, v19
	ds_write2_b32 v26, v21, v18 offset0:152 offset1:220
	v_mov_b32_e32 v18, v19
	s_cbranch_scc1 .LBB0_1148
	v_add3_u32 v16, v20, v139, s95
	v_ashrrev_i32_e32 v17, 31, v16
	v_lshlrev_b64 v[16:17], 8, v[16:17]
	v_lshl_add_u64 v[16:17], v[72:73], 0, v[16:17]
	global_load_dwordx4 v[28:31], v[16:17], off
	global_load_dwordx4 v[24:27], v[16:17], off offset:64
	global_load_dwordx4 v[20:23], v[16:17], off offset:128
	s_nop 0
	global_load_dwordx4 v[16:19], v[16:17], off offset:192
	ds_read_b128 v[56:59], v131
	ds_read_b128 v[60:63], v131 offset:64
	ds_read_b128 v[44:47], v131 offset:4352
	ds_read_b128 v[40:43], v131 offset:4416
	ds_read_b128 v[52:55], v131 offset:128
	ds_read_b128 v[48:51], v131 offset:192
	ds_read_b128 v[36:39], v131 offset:4480
	ds_read_b128 v[32:35], v131 offset:4544
	v_pk_mov_b32 v[124:125], v[120:121], v[120:121] op_sel:[1,0]
	s_movk_i32 s0, 0x1980
	v_mov_b32_e32 v126, v123
.LBB0_1150:
	v_pk_mul_f32 v[126:127], v[124:125], v[126:127] op_sel_hi:[1,0]
	v_add_u32_e32 v147, s0, v65
	v_pk_fma_f32 v[144:145], v[120:121], v[122:123], v[126:127] op_sel_hi:[1,0,1]
	v_pk_fma_f32 v[122:123], v[120:121], v[122:123], v[126:127] op_sel_hi:[1,0,1] neg_lo:[0,0,1] neg_hi:[0,0,1]
	v_cvt_pk_bf16_f32 v146, v122, v145
	v_pk_mul_f32 v[126:127], v[124:125], v[144:145] op_sel:[0,1]
	v_add_u32_e32 v148, 0x400, v147
	v_pk_fma_f32 v[144:145], v[120:121], v[122:123], v[126:127] op_sel_hi:[1,0,1]
	v_pk_fma_f32 v[122:123], v[120:121], v[122:123], v[126:127] op_sel_hi:[1,0,1] neg_lo:[0,0,1] neg_hi:[0,0,1]
	v_cvt_pk_bf16_f32 v126, v122, v145
	ds_write2_b32 v148, v126, v146 offset0:152 offset1:220
	v_pk_mul_f32 v[126:127], v[124:125], v[144:145] op_sel:[0,1]
	s_addk_i32 s0, 0xf780
	v_pk_fma_f32 v[144:145], v[120:121], v[122:123], v[126:127] op_sel_hi:[1,0,1]
	v_pk_fma_f32 v[122:123], v[120:121], v[122:123], v[126:127] op_sel_hi:[1,0,1] neg_lo:[0,0,1] neg_hi:[0,0,1]
	v_cvt_pk_bf16_f32 v146, v122, v145
	v_pk_mul_f32 v[126:127], v[124:125], v[144:145] op_sel:[0,1]
	s_cmpk_lg_i32 s0, 0xf780
	v_pk_fma_f32 v[144:145], v[120:121], v[122:123], v[126:127] op_sel_hi:[1,0,1]
	v_pk_fma_f32 v[122:123], v[120:121], v[122:123], v[126:127] op_sel_hi:[1,0,1] neg_lo:[0,0,1] neg_hi:[0,0,1]
	v_cvt_pk_bf16_f32 v126, v122, v145
	ds_write2_b32 v148, v126, v146 offset0:16 offset1:84
	v_pk_mul_f32 v[126:127], v[124:125], v[144:145] op_sel:[0,1]
	s_nop 0
	v_pk_fma_f32 v[144:145], v[120:121], v[122:123], v[126:127] op_sel_hi:[1,0,1]
	v_pk_fma_f32 v[122:123], v[120:121], v[122:123], v[126:127] op_sel_hi:[1,0,1] neg_lo:[0,0,1] neg_hi:[0,0,1]
	v_cvt_pk_bf16_f32 v146, v122, v145
	v_pk_mul_f32 v[126:127], v[124:125], v[144:145] op_sel:[0,1]
	s_nop 0
	v_pk_fma_f32 v[144:145], v[120:121], v[122:123], v[126:127] op_sel_hi:[1,0,1]
	v_pk_fma_f32 v[122:123], v[120:121], v[122:123], v[126:127] op_sel_hi:[1,0,1] neg_lo:[0,0,1] neg_hi:[0,0,1]
	v_cvt_pk_bf16_f32 v126, v122, v145
	ds_write2_b32 v147, v126, v146 offset0:136 offset1:204
	v_pk_mul_f32 v[126:127], v[124:125], v[144:145] op_sel:[0,1]
	s_nop 0
	v_pk_fma_f32 v[144:145], v[120:121], v[122:123], v[126:127] op_sel_hi:[1,0,1]
	v_pk_fma_f32 v[122:123], v[120:121], v[122:123], v[126:127] op_sel_hi:[1,0,1] neg_lo:[0,0,1] neg_hi:[0,0,1]
	v_bfe_u32 v127, v145, 16, 1
	v_bfe_u32 v126, v122, 16, 1
	v_add3_u32 v126, v122, v126, s89
	v_lshrrev_b32_e32 v126, 16, v126
	v_add3_u32 v127, v145, v127, s89
	v_pk_mul_f32 v[144:145], v[124:125], v[144:145] op_sel:[0,1]
	v_and_or_b32 v146, v127, s75, v126
	v_pk_fma_f32 v[126:127], v[120:121], v[122:123], v[144:145] op_sel_hi:[1,0,1]
	v_pk_fma_f32 v[122:123], v[120:121], v[122:123], v[144:145] op_sel_hi:[1,0,1] neg_lo:[0,0,1] neg_hi:[0,0,1]
	v_cvt_pk_bf16_f32 v123, v122, v127
	v_mov_b32_e32 v126, v127
	ds_write2_b32 v147, v123, v146 offset1:68
	s_cbranch_scc1 .LBB0_1150
	s_waitcnt vmcnt(7) lgkmcnt(11)
	v_mfma_f32_16x16x32_bf16 v[56:59], v[56:59], v[12:15], 0
	v_add_f32_e32 v144, v157, v158
	v_add_f32_e32 v146, v153, v154
	s_waitcnt vmcnt(6) lgkmcnt(10)
	v_mfma_f32_16x16x32_bf16 v[56:59], v[60:63], v[8:11], v[56:59]
	ds_read_b128 v[60:63], v131
	v_add_f32_e32 v145, v159, v160
	v_lshlrev_b32_e32 v128, 1, v128
	s_waitcnt vmcnt(5) lgkmcnt(8)
	v_mfma_f32_16x16x32_bf16 v[52:55], v[52:55], v[4:7], v[56:59]
	v_add_f32_e32 v147, v155, v156
	v_add_f32_e32 v164, v164, v166
	v_add_f32_e32 v161, v161, v162
	ds_read_b128 v[56:59], v131 offset:64
	s_waitcnt vmcnt(4) lgkmcnt(8)
	v_mfma_f32_16x16x32_bf16 v[48:51], v[48:51], v[0:3], v[52:55]
	v_add_f32_e32 v160, v167, v168
	v_add_f32_e32 v162, v163, v165
	s_mov_b32 s0, 0
	ds_read_b128 v[52:55], v131 offset:128
	s_waitcnt vmcnt(3) lgkmcnt(2)
	v_mfma_f32_16x16x32_bf16 v[48:51], v[60:63], v[28:31], v[48:51]
	ds_read_b128 v[60:63], v131 offset:192
	s_waitcnt vmcnt(2) lgkmcnt(2)
	v_mfma_f32_16x16x32_bf16 v[48:51], v[56:59], v[24:27], v[48:51]
	ds_read_b128 v[56:59], v131 offset:4352
	ds_read_b128 v[120:123], v131 offset:4416
	s_waitcnt vmcnt(1) lgkmcnt(3)
	v_mfma_f32_16x16x32_bf16 v[48:51], v[52:55], v[20:23], v[48:51]
	ds_read_b128 v[52:55], v131 offset:4480
	ds_read_b128 v[124:127], v131 offset:4544
	v_mfma_f32_16x16x32_bf16 v[12:15], v[44:47], v[12:15], 0
	s_waitcnt vmcnt(0) lgkmcnt(4)
	v_mfma_f32_16x16x32_bf16 v[48:51], v[60:63], v[16:19], v[48:51]
	v_mfma_f32_16x16x32_bf16 v[8:11], v[40:43], v[8:11], v[12:15]
	v_mfma_f32_16x16x32_bf16 v[4:7], v[36:39], v[4:7], v[8:11]
	s_nop 5
	v_add_f32_e32 v48, v144, v48
	v_fmac_f32_e32 v48, v151, v143
	v_mul_f32_e32 v60, 0x3d372713, v48
	v_mul_f32_e32 v44, v48, v60
	v_fma_f32 v44, v48, v44, v48
	v_mfma_f32_16x16x32_bf16 v[0:3], v[32:35], v[0:3], v[4:7]
	v_mul_f32_e32 v44, 0xbfcc422a, v44
	v_mul_f32_e32 v44, 0x3fb8aa3b, v44
	v_exp_f32_e32 v12, v44
	s_waitcnt lgkmcnt(3)
	v_mfma_f32_16x16x32_bf16 v[0:3], v[56:59], v[28:31], v[0:3]
	v_add_f32_e32 v49, v146, v49
	v_fmac_f32_e32 v49, v152, v143
	v_add_f32_e32 v8, 1.0, v12
	v_rcp_f32_e32 v8, v8
	s_waitcnt lgkmcnt(2)
	v_mfma_f32_16x16x32_bf16 v[0:3], v[120:123], v[24:27], v[0:3]
	v_mul_f32_e32 v61, 0x3d372713, v49
	v_add_f32_e32 v24, v145, v50
	v_mul_f32_e32 v5, v48, v8
	s_waitcnt lgkmcnt(1)
	v_mfma_f32_16x16x32_bf16 v[0:3], v[52:55], v[20:23], v[0:3]
	v_mul_f32_e32 v13, v49, v61
	v_bfe_u32 v6, v5, 16, 1
	v_fmac_f32_e32 v24, v150, v143
	v_fma_f32 v13, v49, v13, v49
	v_add3_u32 v5, v5, v6, s89
	v_mul_f32_e32 v6, 0x3d372713, v24
	v_mul_f32_e32 v9, 0xbfcc422a, v13
	v_mul_f32_e32 v6, v24, v6
	v_mul_f32_e32 v4, 0x3fb8aa3b, v9
	s_waitcnt lgkmcnt(0)
	v_mfma_f32_16x16x32_bf16 v[16:19], v[124:127], v[16:19], v[0:3]
	v_exp_f32_e32 v4, v4
	v_lshlrev_b32_e32 v120, 4, v142
	v_ashrrev_i32_e32 v121, 31, v120
	v_fma_f32 v0, v24, v6, v24
	v_mul_f32_e32 v0, 0xbfcc422a, v0
	v_mul_f32_e32 v0, 0x3fb8aa3b, v0
	v_exp_f32_e32 v0, v0
	v_add_f32_e32 v4, 1.0, v4
	v_rcp_f32_e32 v4, v4
	v_add3_u32 v28, v130, v128, v132
	v_add_f32_e32 v0, 1.0, v0
	v_rcp_f32_e32 v23, v0
	v_lshlrev_b64 v[0:1], 2, v[120:121]
	v_lshl_add_u64 v[2:3], v[76:77], 0, v[0:1]
	ds_write_b16_d16_hi v28, v5 offset:34816
	v_mul_f32_e32 v21, v49, v4
	v_lshl_add_u64 v[4:5], v[2:3], 0, v[80:81]
	v_add_f32_e32 v25, v147, v51
	v_lshl_add_u64 v[0:1], v[78:79], 0, v[0:1]
	v_add_co_u32_e32 v6, vcc, s92, v4
	v_fmac_f32_e32 v25, v149, v143
	s_nop 0
	v_addc_co_u32_e32 v7, vcc, 0, v5, vcc
	global_load_dword v148, v[4:5], off
	global_load_dword v149, v[6:7], off
	v_lshl_add_u64 v[4:5], v[0:1], 0, v[82:83]
	global_load_dword v128, v[4:5], off
	v_lshl_add_u64 v[4:5], v[2:3], 0, v[84:85]
	v_add_co_u32_e32 v6, vcc, s92, v4
	v_add_u32_e32 v20, s5, v120
	s_nop 0
	v_addc_co_u32_e32 v7, vcc, 0, v5, vcc
	global_load_dword v144, v[4:5], off
	global_load_dword v145, v[6:7], off
	v_lshl_add_u64 v[4:5], v[0:1], 0, v[86:87]
	global_load_dword v142, v[4:5], off
	v_lshl_add_u64 v[4:5], v[2:3], 0, v[88:89]
	v_add_co_u32_e32 v6, vcc, s92, v4
	v_mul_f32_e32 v26, 0x3d372713, v25
	s_nop 0
	v_addc_co_u32_e32 v7, vcc, 0, v5, vcc
	global_load_dword v150, v[4:5], off
	global_load_dword v151, v[6:7], off
	v_lshl_add_u64 v[4:5], v[0:1], 0, v[90:91]
	global_load_dword v127, v[4:5], off
	v_lshl_add_u64 v[4:5], v[2:3], 0, v[92:93]
	v_add_co_u32_e32 v6, vcc, s92, v4
	v_mul_f32_e32 v26, v25, v26
	s_nop 0
	v_addc_co_u32_e32 v7, vcc, 0, v5, vcc
	global_load_dword v146, v[4:5], off
	global_load_dword v147, v[6:7], off
	v_lshl_add_u64 v[4:5], v[0:1], 0, v[94:95]
	global_load_dword v126, v[4:5], off
	v_lshl_add_u64 v[4:5], v[2:3], 0, v[96:97]
	v_add_co_u32_e32 v6, vcc, s92, v4
	v_fma_f32 v26, v25, v26, v25
	s_nop 0
	v_addc_co_u32_e32 v7, vcc, 0, v5, vcc
	global_load_dword v155, v[4:5], off
	global_load_dword v157, v[6:7], off
	v_lshl_add_u64 v[4:5], v[0:1], 0, v[98:99]
	global_load_dword v124, v[4:5], off
	v_lshl_add_u64 v[4:5], v[2:3], 0, v[100:101]
	v_add_co_u32_e32 v6, vcc, s92, v4
	v_mul_f32_e32 v26, 0xbfcc422a, v26
	s_nop 0
	v_addc_co_u32_e32 v7, vcc, 0, v5, vcc
	global_load_dword v152, v[4:5], off
	global_load_dword v153, v[6:7], off
	v_lshl_add_u64 v[4:5], v[0:1], 0, v[102:103]
	global_load_dword v123, v[4:5], off
	v_lshl_add_u64 v[4:5], v[2:3], 0, v[104:105]
	v_add_co_u32_e32 v6, vcc, s92, v4
	v_lshl_add_u64 v[2:3], v[2:3], 0, v[110:111]
	s_nop 0
	v_addc_co_u32_e32 v7, vcc, 0, v5, vcc
	global_load_dword v158, v[4:5], off
	global_load_dword v159, v[6:7], off
	v_lshl_add_u64 v[4:5], v[0:1], 0, v[106:107]
	global_load_dword v121, v[4:5], off
	v_add_co_u32_e32 v4, vcc, s92, v2
	v_lshl_add_u64 v[0:1], v[0:1], 0, v[108:109]
	s_nop 0
	v_addc_co_u32_e32 v5, vcc, 0, v3, vcc
	global_load_dword v154, v[2:3], off
	global_load_dword v156, v[4:5], off
	ds_read_b64 v[2:3], v229 offset:63640
	global_load_dword v122, v[0:1], off
	v_add_u32_e32 v0, v120, v140
	v_ashrrev_i32_e32 v1, 31, v0
	v_mul_f32_e32 v26, 0x3fb8aa3b, v26
	s_waitcnt lgkmcnt(0)
	v_lshl_add_u64 v[0:1], v[0:1], 2, v[2:3]
	global_load_dword v125, v[0:1], off
	v_or_b32_e32 v0, v20, v139
	v_ashrrev_i32_e32 v1, 31, v0
	v_lshlrev_b64 v[0:1], 8, v[0:1]
	v_lshl_add_u64 v[0:1], v[72:73], 0, v[0:1]
	global_load_dwordx4 v[12:15], v[0:1], off
	global_load_dwordx4 v[8:11], v[0:1], off offset:64
	global_load_dwordx4 v[4:7], v[0:1], off offset:128
	s_nop 0
	global_load_dwordx4 v[0:3], v[0:1], off offset:192
	v_exp_f32_e32 v26, v26
	v_bfe_u32 v22, v21, 16, 1
	v_add3_u32 v21, v21, v22, s89
	ds_write_b16_d16_hi v28, v21 offset:35344
	v_add_f32_e32 v22, 1.0, v26
	v_rcp_f32_e32 v22, v22
	v_mul_f32_e32 v21, v24, v23
	v_bfe_u32 v23, v21, 16, 1
	v_add_f32_e32 v16, v164, v16
	v_add3_u32 v21, v21, v23, s89
	v_fmac_f32_e32 v16, v135, v143
	ds_write_b16_d16_hi v28, v21 offset:35872
	v_mul_f32_e32 v21, v25, v22
	v_mul_f32_e32 v22, 0x3d372713, v16
	v_mul_f32_e32 v22, v16, v22
	v_fma_f32 v22, v16, v22, v16
	v_mul_f32_e32 v22, 0xbfcc422a, v22
	v_mul_f32_e32 v22, 0x3fb8aa3b, v22
	v_exp_f32_e32 v22, v22
	v_bfe_u32 v23, v21, 16, 1
	v_add_f32_e32 v17, v161, v17
	v_add3_u32 v21, v21, v23, s89
	v_fmac_f32_e32 v17, v134, v143
	ds_write_b16_d16_hi v28, v21 offset:36400
	v_add_f32_e32 v21, 1.0, v22
	v_mul_f32_e32 v22, 0x3d372713, v17
	v_mul_f32_e32 v22, v17, v22
	v_fma_f32 v22, v17, v22, v17
	v_rcp_f32_e32 v21, v21
	v_mul_f32_e32 v22, 0xbfcc422a, v22
	v_mul_f32_e32 v22, 0x3fb8aa3b, v22
	v_exp_f32_e32 v22, v22
	v_mul_f32_e32 v16, v16, v21
	v_add_f32_e32 v18, v160, v18
	v_bfe_u32 v21, v16, 16, 1
	v_fmac_f32_e32 v18, v129, v143
	v_add3_u32 v16, v16, v21, s89
	v_add_f32_e32 v21, 1.0, v22
	v_mul_f32_e32 v22, 0x3d372713, v18
	v_mul_f32_e32 v22, v18, v22
	v_fma_f32 v22, v18, v22, v18
	v_mul_f32_e32 v22, 0xbfcc422a, v22
	v_mul_f32_e32 v22, 0x3fb8aa3b, v22
	v_rcp_f32_e32 v21, v21
	v_exp_f32_e32 v22, v22
	v_add_f32_e32 v19, v162, v19
	v_fmac_f32_e32 v19, v133, v143
	ds_write_b16_d16_hi v28, v16 offset:43264
	v_mul_f32_e32 v16, v17, v21
	v_add_f32_e32 v21, 1.0, v22
	v_mul_f32_e32 v22, 0x3d372713, v19
	v_mul_f32_e32 v22, v19, v22
	v_fma_f32 v22, v19, v22, v19
	v_mul_f32_e32 v22, 0xbfcc422a, v22
	v_mul_f32_e32 v22, 0x3fb8aa3b, v22
	v_exp_f32_e32 v22, v22
	v_rcp_f32_e32 v21, v21
	v_bfe_u32 v17, v16, 16, 1
	v_add3_u32 v16, v16, v17, s89
	v_add_f32_e32 v17, 1.0, v22
	v_rcp_f32_e32 v17, v17
	ds_write_b16_d16_hi v28, v16 offset:43792
	v_mul_f32_e32 v16, v18, v21
	v_bfe_u32 v18, v16, 16, 1
	v_add3_u32 v16, v16, v18, s89
	ds_write_b16_d16_hi v28, v16 offset:44320
	v_mul_f32_e32 v16, v19, v17
	v_bfe_u32 v17, v16, 16, 1
	v_add3_u32 v16, v16, v17, s89
	ds_write_b16_d16_hi v28, v16 offset:44848
	v_pk_mov_b32 v[16:17], v[116:117], v[116:117] op_sel:[1,0]
	v_mov_b32_e32 v18, v119
.LBB0_1152:
	v_pk_mul_f32 v[18:19], v[16:17], v[18:19] op_sel_hi:[1,0]
	v_add_u32_e32 v26, s0, v65
	v_pk_fma_f32 v[22:23], v[116:117], v[118:119], v[18:19] op_sel_hi:[1,0,1]
	v_pk_fma_f32 v[18:19], v[116:117], v[118:119], v[18:19] op_sel_hi:[1,0,1] neg_lo:[0,0,1] neg_hi:[0,0,1]
	v_bfe_u32 v24, v23, 16, 1
	v_bfe_u32 v21, v18, 16, 1
	v_add3_u32 v21, v18, v21, s89
	v_lshrrev_b32_e32 v21, 16, v21
	v_add3_u32 v24, v23, v24, s89
	v_pk_mul_f32 v[22:23], v[16:17], v[22:23] op_sel:[0,1]
	v_and_or_b32 v21, v24, s75, v21
	v_pk_fma_f32 v[24:25], v[116:117], v[18:19], v[22:23] op_sel_hi:[1,0,1]
	v_pk_fma_f32 v[18:19], v[116:117], v[18:19], v[22:23] op_sel_hi:[1,0,1] neg_lo:[0,0,1] neg_hi:[0,0,1]
	v_cvt_pk_bf16_f32 v22, v18, v25
	ds_write2_b32 v26, v21, v22 offset1:68
	v_pk_mul_f32 v[22:23], v[16:17], v[24:25] op_sel:[0,1]
	s_addk_i32 s0, 0x880
	v_pk_fma_f32 v[24:25], v[116:117], v[18:19], v[22:23] op_sel_hi:[1,0,1]
	v_pk_fma_f32 v[18:19], v[116:117], v[18:19], v[22:23] op_sel_hi:[1,0,1] neg_lo:[0,0,1] neg_hi:[0,0,1]
	v_cvt_pk_bf16_f32 v21, v18, v25
	v_pk_mul_f32 v[22:23], v[16:17], v[24:25] op_sel:[0,1]
	s_cmpk_lg_i32 s0, 0x2200
	v_pk_fma_f32 v[24:25], v[116:117], v[18:19], v[22:23] op_sel_hi:[1,0,1]
	v_pk_fma_f32 v[18:19], v[116:117], v[18:19], v[22:23] op_sel_hi:[1,0,1] neg_lo:[0,0,1] neg_hi:[0,0,1]
	v_cvt_pk_bf16_f32 v22, v18, v25
	ds_write2_b32 v26, v21, v22 offset0:136 offset1:204
	v_pk_mul_f32 v[22:23], v[16:17], v[24:25] op_sel:[0,1]
	v_add_u32_e32 v26, 0x400, v26
	v_pk_fma_f32 v[24:25], v[116:117], v[18:19], v[22:23] op_sel_hi:[1,0,1]
	v_pk_fma_f32 v[18:19], v[116:117], v[18:19], v[22:23] op_sel_hi:[1,0,1] neg_lo:[0,0,1] neg_hi:[0,0,1]
	v_cvt_pk_bf16_f32 v21, v18, v25
	v_pk_mul_f32 v[22:23], v[16:17], v[24:25] op_sel:[0,1]
	s_nop 0
	v_pk_fma_f32 v[24:25], v[116:117], v[18:19], v[22:23] op_sel_hi:[1,0,1]
	v_pk_fma_f32 v[18:19], v[116:117], v[18:19], v[22:23] op_sel_hi:[1,0,1] neg_lo:[0,0,1] neg_hi:[0,0,1]
	v_cvt_pk_bf16_f32 v22, v18, v25
	ds_write2_b32 v26, v21, v22 offset0:16 offset1:84
	v_pk_mul_f32 v[22:23], v[16:17], v[24:25] op_sel:[0,1]
	s_nop 0
	v_pk_fma_f32 v[24:25], v[116:117], v[18:19], v[22:23] op_sel_hi:[1,0,1]
	v_pk_fma_f32 v[22:23], v[116:117], v[18:19], v[22:23] op_sel_hi:[1,0,1] neg_lo:[0,0,1] neg_hi:[0,0,1]
	v_bfe_u32 v19, v25, 16, 1
	v_bfe_u32 v18, v22, 16, 1
	v_add3_u32 v18, v22, v18, s89
	v_lshrrev_b32_e32 v18, 16, v18
	v_add3_u32 v19, v25, v19, s89
	v_pk_mul_f32 v[24:25], v[16:17], v[24:25] op_sel:[0,1]
	v_and_or_b32 v21, v19, s75, v18
	v_pk_fma_f32 v[18:19], v[116:117], v[22:23], v[24:25] op_sel_hi:[1,0,1]
	v_pk_fma_f32 v[118:119], v[116:117], v[22:23], v[24:25] op_sel_hi:[1,0,1] neg_lo:[0,0,1] neg_hi:[0,0,1]
	v_cvt_pk_bf16_f32 v18, v118, v19
	ds_write2_b32 v26, v21, v18 offset0:152 offset1:220
	v_mov_b32_e32 v18, v19
	s_cbranch_scc1 .LBB0_1152
	v_add3_u32 v16, v20, v139, s95
	v_ashrrev_i32_e32 v17, 31, v16
	v_lshlrev_b64 v[16:17], 8, v[16:17]
	v_lshl_add_u64 v[16:17], v[72:73], 0, v[16:17]
	global_load_dwordx4 v[28:31], v[16:17], off
	global_load_dwordx4 v[24:27], v[16:17], off offset:64
	global_load_dwordx4 v[20:23], v[16:17], off offset:128
	s_nop 0
	global_load_dwordx4 v[16:19], v[16:17], off offset:192
	ds_read_b128 v[56:59], v131
	ds_read_b128 v[60:63], v131 offset:64
	ds_read_b128 v[44:47], v131 offset:4352
	ds_read_b128 v[40:43], v131 offset:4416
	ds_read_b128 v[52:55], v131 offset:128
	ds_read_b128 v[48:51], v131 offset:192
	ds_read_b128 v[36:39], v131 offset:4480
	ds_read_b128 v[32:35], v131 offset:4544
	v_pk_mov_b32 v[116:117], v[112:113], v[112:113] op_sel:[1,0]
	s_movk_i32 s0, 0x1980
	v_mov_b32_e32 v118, v115
.LBB0_1154:
	v_pk_mul_f32 v[118:119], v[116:117], v[118:119] op_sel_hi:[1,0]
	v_add_u32_e32 v133, s0, v65
	v_pk_fma_f32 v[134:135], v[112:113], v[114:115], v[118:119] op_sel_hi:[1,0,1]
	v_pk_fma_f32 v[114:115], v[112:113], v[114:115], v[118:119] op_sel_hi:[1,0,1] neg_lo:[0,0,1] neg_hi:[0,0,1]
	v_cvt_pk_bf16_f32 v129, v114, v135
	v_pk_mul_f32 v[118:119], v[116:117], v[134:135] op_sel:[0,1]
	v_add_u32_e32 v143, 0x400, v133
	v_pk_fma_f32 v[134:135], v[112:113], v[114:115], v[118:119] op_sel_hi:[1,0,1]
	v_pk_fma_f32 v[114:115], v[112:113], v[114:115], v[118:119] op_sel_hi:[1,0,1] neg_lo:[0,0,1] neg_hi:[0,0,1]
	v_cvt_pk_bf16_f32 v118, v114, v135
	ds_write2_b32 v143, v118, v129 offset0:152 offset1:220
	v_pk_mul_f32 v[118:119], v[116:117], v[134:135] op_sel:[0,1]
	s_addk_i32 s0, 0xf780
	v_pk_fma_f32 v[134:135], v[112:113], v[114:115], v[118:119] op_sel_hi:[1,0,1]
	v_pk_fma_f32 v[114:115], v[112:113], v[114:115], v[118:119] op_sel_hi:[1,0,1] neg_lo:[0,0,1] neg_hi:[0,0,1]
	v_cvt_pk_bf16_f32 v129, v114, v135
	v_pk_mul_f32 v[118:119], v[116:117], v[134:135] op_sel:[0,1]
	s_cmpk_lg_i32 s0, 0xf780
	v_pk_fma_f32 v[134:135], v[112:113], v[114:115], v[118:119] op_sel_hi:[1,0,1]
	v_pk_fma_f32 v[114:115], v[112:113], v[114:115], v[118:119] op_sel_hi:[1,0,1] neg_lo:[0,0,1] neg_hi:[0,0,1]
	v_cvt_pk_bf16_f32 v118, v114, v135
	ds_write2_b32 v143, v118, v129 offset0:16 offset1:84
	v_pk_mul_f32 v[118:119], v[116:117], v[134:135] op_sel:[0,1]
	s_nop 0
	v_pk_fma_f32 v[134:135], v[112:113], v[114:115], v[118:119] op_sel_hi:[1,0,1]
	v_pk_fma_f32 v[114:115], v[112:113], v[114:115], v[118:119] op_sel_hi:[1,0,1] neg_lo:[0,0,1] neg_hi:[0,0,1]
	v_cvt_pk_bf16_f32 v129, v114, v135
	v_pk_mul_f32 v[118:119], v[116:117], v[134:135] op_sel:[0,1]
	s_nop 0
	v_pk_fma_f32 v[134:135], v[112:113], v[114:115], v[118:119] op_sel_hi:[1,0,1]
	v_pk_fma_f32 v[114:115], v[112:113], v[114:115], v[118:119] op_sel_hi:[1,0,1] neg_lo:[0,0,1] neg_hi:[0,0,1]
	v_cvt_pk_bf16_f32 v118, v114, v135
	ds_write2_b32 v133, v118, v129 offset0:136 offset1:204
	v_pk_mul_f32 v[118:119], v[116:117], v[134:135] op_sel:[0,1]
	s_nop 0
	v_pk_fma_f32 v[134:135], v[112:113], v[114:115], v[118:119] op_sel_hi:[1,0,1]
	v_pk_fma_f32 v[114:115], v[112:113], v[114:115], v[118:119] op_sel_hi:[1,0,1] neg_lo:[0,0,1] neg_hi:[0,0,1]
	v_bfe_u32 v119, v135, 16, 1
	v_bfe_u32 v118, v114, 16, 1
	v_add3_u32 v118, v114, v118, s89
	v_lshrrev_b32_e32 v118, 16, v118
	v_add3_u32 v119, v135, v119, s89
	v_pk_mul_f32 v[134:135], v[116:117], v[134:135] op_sel:[0,1]
	v_and_or_b32 v129, v119, s75, v118
	v_pk_fma_f32 v[118:119], v[112:113], v[114:115], v[134:135] op_sel_hi:[1,0,1]
	v_pk_fma_f32 v[114:115], v[112:113], v[114:115], v[134:135] op_sel_hi:[1,0,1] neg_lo:[0,0,1] neg_hi:[0,0,1]
	v_cvt_pk_bf16_f32 v115, v114, v119
	v_mov_b32_e32 v118, v119
	ds_write2_b32 v133, v115, v129 offset1:68
	s_cbranch_scc1 .LBB0_1154
	s_waitcnt vmcnt(7) lgkmcnt(11)
	v_mfma_f32_16x16x32_bf16 v[56:59], v[56:59], v[12:15], 0
	v_add_f32_e32 v129, v148, v149
	v_add_f32_e32 v143, v144, v145
	s_waitcnt vmcnt(6) lgkmcnt(10)
	v_mfma_f32_16x16x32_bf16 v[56:59], v[60:63], v[8:11], v[56:59]
	ds_read_b128 v[60:63], v131
	v_add_f32_e32 v134, v150, v151
	v_lshlrev_b32_e32 v120, 1, v120
	s_waitcnt vmcnt(5) lgkmcnt(8)
	v_mfma_f32_16x16x32_bf16 v[52:55], v[52:55], v[4:7], v[56:59]
	v_add_f32_e32 v144, v146, v147
	v_add_f32_e32 v133, v155, v157
	v_add_f32_e32 v145, v152, v153
	ds_read_b128 v[56:59], v131 offset:64
	s_waitcnt vmcnt(4) lgkmcnt(8)
	v_mfma_f32_16x16x32_bf16 v[48:51], v[48:51], v[0:3], v[52:55]
	v_add_f32_e32 v135, v158, v159
	v_add_f32_e32 v146, v154, v156
	s_mov_b32 s0, 0
	ds_read_b128 v[52:55], v131 offset:128
	s_waitcnt vmcnt(3) lgkmcnt(2)
	v_mfma_f32_16x16x32_bf16 v[48:51], v[60:63], v[28:31], v[48:51]
	ds_read_b128 v[60:63], v131 offset:192
	s_waitcnt vmcnt(2) lgkmcnt(2)
	v_mfma_f32_16x16x32_bf16 v[48:51], v[56:59], v[24:27], v[48:51]
	ds_read_b128 v[56:59], v131 offset:4352
	ds_read_b128 v[112:115], v131 offset:4416
	s_waitcnt vmcnt(1) lgkmcnt(3)
	v_mfma_f32_16x16x32_bf16 v[48:51], v[52:55], v[20:23], v[48:51]
	ds_read_b128 v[52:55], v131 offset:4480
	ds_read_b128 v[116:119], v131 offset:4544
	v_mfma_f32_16x16x32_bf16 v[12:15], v[44:47], v[12:15], 0
	s_waitcnt vmcnt(0) lgkmcnt(4)
	v_mfma_f32_16x16x32_bf16 v[48:51], v[60:63], v[16:19], v[48:51]
	v_mfma_f32_16x16x32_bf16 v[8:11], v[40:43], v[8:11], v[12:15]
	v_mfma_f32_16x16x32_bf16 v[4:7], v[36:39], v[4:7], v[8:11]
	s_nop 5
	v_add_f32_e32 v48, v129, v48
	v_fmac_f32_e32 v48, v128, v125
	v_mul_f32_e32 v60, 0x3d372713, v48
	v_mul_f32_e32 v44, v48, v60
	v_fma_f32 v44, v48, v44, v48
	v_mfma_f32_16x16x32_bf16 v[0:3], v[32:35], v[0:3], v[4:7]
	v_mul_f32_e32 v44, 0xbfcc422a, v44
	v_mul_f32_e32 v44, 0x3fb8aa3b, v44
	v_exp_f32_e32 v12, v44
	s_waitcnt lgkmcnt(3)
	v_mfma_f32_16x16x32_bf16 v[0:3], v[56:59], v[28:31], v[0:3]
	v_add_f32_e32 v49, v143, v49
	v_fmac_f32_e32 v49, v142, v125
	v_add_f32_e32 v8, 1.0, v12
	v_rcp_f32_e32 v8, v8
	s_waitcnt lgkmcnt(2)
	v_mfma_f32_16x16x32_bf16 v[0:3], v[112:115], v[24:27], v[0:3]
	v_mul_f32_e32 v61, 0x3d372713, v49
	v_add_f32_e32 v24, v134, v50
	v_mul_f32_e32 v5, v48, v8
	s_waitcnt lgkmcnt(1)
	v_mfma_f32_16x16x32_bf16 v[0:3], v[52:55], v[20:23], v[0:3]
	v_mul_f32_e32 v13, v49, v61
	v_bfe_u32 v6, v5, 16, 1
	v_fmac_f32_e32 v24, v127, v125
	v_fma_f32 v13, v49, v13, v49
	v_add3_u32 v5, v5, v6, s89
	v_mul_f32_e32 v6, 0x3d372713, v24
	v_mul_f32_e32 v9, 0xbfcc422a, v13
	v_mul_f32_e32 v6, v24, v6
	v_mul_f32_e32 v4, 0x3fb8aa3b, v9
	s_waitcnt lgkmcnt(0)
	v_mfma_f32_16x16x32_bf16 v[16:19], v[116:119], v[16:19], v[0:3]
	v_exp_f32_e32 v4, v4
	v_lshlrev_b32_e32 v112, 4, v141
	v_ashrrev_i32_e32 v113, 31, v112
	v_fma_f32 v0, v24, v6, v24
	v_mul_f32_e32 v0, 0xbfcc422a, v0
	v_mul_f32_e32 v0, 0x3fb8aa3b, v0
	v_exp_f32_e32 v0, v0
	v_add_f32_e32 v4, 1.0, v4
	v_rcp_f32_e32 v4, v4
	v_add3_u32 v28, v130, v120, v132
	v_add_f32_e32 v0, 1.0, v0
	v_rcp_f32_e32 v23, v0
	v_lshlrev_b64 v[0:1], 2, v[112:113]
	v_lshl_add_u64 v[2:3], v[76:77], 0, v[0:1]
	ds_write_b16_d16_hi v28, v5 offset:34816
	v_mul_f32_e32 v21, v49, v4
	v_lshl_add_u64 v[4:5], v[2:3], 0, v[80:81]
	v_lshl_add_u64 v[0:1], v[78:79], 0, v[0:1]
	v_add_co_u32_e32 v6, vcc, s92, v4
	v_add_u32_e32 v20, s5, v112
	s_nop 0
	v_addc_co_u32_e32 v7, vcc, 0, v5, vcc
	global_load_dword v114, v[4:5], off
	global_load_dword v115, v[6:7], off
	v_lshl_add_u64 v[4:5], v[0:1], 0, v[82:83]
	global_load_dword v113, v[4:5], off
	v_lshl_add_u64 v[4:5], v[2:3], 0, v[84:85]
	v_add_co_u32_e32 v6, vcc, s92, v4
	v_add_f32_e32 v25, v144, v51
	s_nop 0
	v_addc_co_u32_e32 v7, vcc, 0, v5, vcc
	global_load_dword v84, v[4:5], off
	global_load_dword v85, v[6:7], off
	v_lshl_add_u64 v[4:5], v[0:1], 0, v[86:87]
	global_load_dword v83, v[4:5], off
	v_lshl_add_u64 v[4:5], v[2:3], 0, v[88:89]
	v_add_co_u32_e32 v6, vcc, s92, v4
	v_fmac_f32_e32 v25, v126, v125
	s_nop 0
	v_addc_co_u32_e32 v7, vcc, 0, v5, vcc
	global_load_dword v86, v[4:5], off
	global_load_dword v87, v[6:7], off
	v_lshl_add_u64 v[4:5], v[0:1], 0, v[90:91]
	global_load_dword v82, v[4:5], off
	v_lshl_add_u64 v[4:5], v[2:3], 0, v[92:93]
	v_add_co_u32_e32 v6, vcc, s92, v4
	v_mul_f32_e32 v26, 0x3d372713, v25
	s_nop 0
	v_addc_co_u32_e32 v7, vcc, 0, v5, vcc
	global_load_dword v88, v[4:5], off
	global_load_dword v89, v[6:7], off
	v_lshl_add_u64 v[4:5], v[0:1], 0, v[94:95]
	global_load_dword v81, v[4:5], off
	v_lshl_add_u64 v[4:5], v[2:3], 0, v[96:97]
	v_add_co_u32_e32 v6, vcc, s92, v4
	v_mul_f32_e32 v26, v25, v26
	s_nop 0
	v_addc_co_u32_e32 v7, vcc, 0, v5, vcc
	global_load_dword v90, v[4:5], off
	global_load_dword v91, v[6:7], off
	v_lshl_add_u64 v[4:5], v[0:1], 0, v[98:99]
	global_load_dword v80, v[4:5], off
	v_lshl_add_u64 v[4:5], v[2:3], 0, v[100:101]
	v_add_co_u32_e32 v6, vcc, s92, v4
	v_fma_f32 v26, v25, v26, v25
	s_nop 0
	v_addc_co_u32_e32 v7, vcc, 0, v5, vcc
	global_load_dword v92, v[4:5], off
	global_load_dword v93, v[6:7], off
	v_lshl_add_u64 v[4:5], v[0:1], 0, v[102:103]
	global_load_dword v79, v[4:5], off
	v_lshl_add_u64 v[4:5], v[2:3], 0, v[104:105]
	v_add_co_u32_e32 v6, vcc, s92, v4
	v_lshl_add_u64 v[2:3], v[2:3], 0, v[110:111]
	s_nop 0
	v_addc_co_u32_e32 v7, vcc, 0, v5, vcc
	global_load_dword v94, v[4:5], off
	global_load_dword v95, v[6:7], off
	v_lshl_add_u64 v[4:5], v[0:1], 0, v[106:107]
	global_load_dword v78, v[4:5], off
	v_add_co_u32_e32 v4, vcc, s92, v2
	v_lshl_add_u64 v[0:1], v[0:1], 0, v[108:109]
	s_nop 0
	v_addc_co_u32_e32 v5, vcc, 0, v3, vcc
	global_load_dword v96, v[2:3], off
	global_load_dword v97, v[4:5], off
	ds_read_b64 v[2:3], v229 offset:63640
	global_load_dword v76, v[0:1], off
	v_add_u32_e32 v0, v112, v140
	v_ashrrev_i32_e32 v1, 31, v0
	v_mul_f32_e32 v26, 0xbfcc422a, v26
	s_waitcnt lgkmcnt(0)
	v_lshl_add_u64 v[0:1], v[0:1], 2, v[2:3]
	global_load_dword v77, v[0:1], off
	v_or_b32_e32 v0, v20, v139
	v_ashrrev_i32_e32 v1, 31, v0
	v_lshlrev_b64 v[0:1], 8, v[0:1]
	v_lshl_add_u64 v[0:1], v[72:73], 0, v[0:1]
	global_load_dwordx4 v[12:15], v[0:1], off
	global_load_dwordx4 v[8:11], v[0:1], off offset:64
	global_load_dwordx4 v[4:7], v[0:1], off offset:128
	s_nop 0
	global_load_dwordx4 v[0:3], v[0:1], off offset:192
	v_mul_f32_e32 v26, 0x3fb8aa3b, v26
	v_exp_f32_e32 v26, v26
	v_bfe_u32 v22, v21, 16, 1
	v_add3_u32 v21, v21, v22, s89
	ds_write_b16_d16_hi v28, v21 offset:35344
	v_add_f32_e32 v22, 1.0, v26
	v_rcp_f32_e32 v22, v22
	v_mul_f32_e32 v21, v24, v23
	v_bfe_u32 v23, v21, 16, 1
	v_add_f32_e32 v16, v133, v16
	v_add3_u32 v21, v21, v23, s89
	v_fmac_f32_e32 v16, v124, v125
	ds_write_b16_d16_hi v28, v21 offset:35872
	v_mul_f32_e32 v21, v25, v22
	v_mul_f32_e32 v22, 0x3d372713, v16
	v_mul_f32_e32 v22, v16, v22
	v_fma_f32 v22, v16, v22, v16
	v_mul_f32_e32 v22, 0xbfcc422a, v22
	v_mul_f32_e32 v22, 0x3fb8aa3b, v22
	v_exp_f32_e32 v22, v22
	v_bfe_u32 v23, v21, 16, 1
	v_add_f32_e32 v17, v145, v17
	v_add3_u32 v21, v21, v23, s89
	v_fmac_f32_e32 v17, v123, v125
	ds_write_b16_d16_hi v28, v21 offset:36400
	v_add_f32_e32 v21, 1.0, v22
	v_mul_f32_e32 v22, 0x3d372713, v17
	v_mul_f32_e32 v22, v17, v22
	v_fma_f32 v22, v17, v22, v17
	v_rcp_f32_e32 v21, v21
	v_mul_f32_e32 v22, 0xbfcc422a, v22
	v_mul_f32_e32 v22, 0x3fb8aa3b, v22
	v_exp_f32_e32 v22, v22
	v_mul_f32_e32 v16, v16, v21
	v_add_f32_e32 v18, v135, v18
	v_bfe_u32 v21, v16, 16, 1
	v_fmac_f32_e32 v18, v121, v125
	v_add3_u32 v16, v16, v21, s89
	v_add_f32_e32 v21, 1.0, v22
	v_mul_f32_e32 v22, 0x3d372713, v18
	v_mul_f32_e32 v22, v18, v22
	v_fma_f32 v22, v18, v22, v18
	v_mul_f32_e32 v22, 0xbfcc422a, v22
	v_mul_f32_e32 v22, 0x3fb8aa3b, v22
	v_rcp_f32_e32 v21, v21
	v_exp_f32_e32 v22, v22
	v_add_f32_e32 v19, v146, v19
	v_fmac_f32_e32 v19, v122, v125
	ds_write_b16_d16_hi v28, v16 offset:43264
	v_mul_f32_e32 v16, v17, v21
	v_add_f32_e32 v21, 1.0, v22
	v_mul_f32_e32 v22, 0x3d372713, v19
	v_mul_f32_e32 v22, v19, v22
	v_fma_f32 v22, v19, v22, v19
	v_mul_f32_e32 v22, 0xbfcc422a, v22
	v_mul_f32_e32 v22, 0x3fb8aa3b, v22
	v_exp_f32_e32 v22, v22
	v_rcp_f32_e32 v21, v21
	v_bfe_u32 v17, v16, 16, 1
	v_add3_u32 v16, v16, v17, s89
	v_add_f32_e32 v17, 1.0, v22
	v_rcp_f32_e32 v17, v17
	ds_write_b16_d16_hi v28, v16 offset:43792
	v_mul_f32_e32 v16, v18, v21
	v_bfe_u32 v18, v16, 16, 1
	v_add3_u32 v16, v16, v18, s89
	ds_write_b16_d16_hi v28, v16 offset:44320
	v_mul_f32_e32 v16, v19, v17
	v_bfe_u32 v17, v16, 16, 1
	v_add3_u32 v16, v16, v17, s89
	ds_write_b16_d16_hi v28, v16 offset:44848
	v_pk_mov_b32 v[16:17], v[70:71], v[70:71] op_sel:[1,0]
	v_mov_b32_e32 v18, v75
.LBB0_1156:
	v_pk_mul_f32 v[18:19], v[16:17], v[18:19] op_sel_hi:[1,0]
	v_add_u32_e32 v26, s0, v65
	v_pk_fma_f32 v[22:23], v[70:71], v[74:75], v[18:19] op_sel_hi:[1,0,1]
	v_pk_fma_f32 v[18:19], v[70:71], v[74:75], v[18:19] op_sel_hi:[1,0,1] neg_lo:[0,0,1] neg_hi:[0,0,1]
	v_bfe_u32 v24, v23, 16, 1
	v_bfe_u32 v21, v18, 16, 1
	v_add3_u32 v21, v18, v21, s89
	v_lshrrev_b32_e32 v21, 16, v21
	v_add3_u32 v24, v23, v24, s89
	v_pk_mul_f32 v[22:23], v[16:17], v[22:23] op_sel:[0,1]
	v_and_or_b32 v21, v24, s75, v21
	v_pk_fma_f32 v[24:25], v[70:71], v[18:19], v[22:23] op_sel_hi:[1,0,1]
	v_pk_fma_f32 v[18:19], v[70:71], v[18:19], v[22:23] op_sel_hi:[1,0,1] neg_lo:[0,0,1] neg_hi:[0,0,1]
	v_cvt_pk_bf16_f32 v22, v18, v25
	ds_write2_b32 v26, v21, v22 offset1:68
	v_pk_mul_f32 v[22:23], v[16:17], v[24:25] op_sel:[0,1]
	s_addk_i32 s0, 0x880
	v_pk_fma_f32 v[24:25], v[70:71], v[18:19], v[22:23] op_sel_hi:[1,0,1]
	v_pk_fma_f32 v[18:19], v[70:71], v[18:19], v[22:23] op_sel_hi:[1,0,1] neg_lo:[0,0,1] neg_hi:[0,0,1]
	v_cvt_pk_bf16_f32 v21, v18, v25
	v_pk_mul_f32 v[22:23], v[16:17], v[24:25] op_sel:[0,1]
	s_cmpk_lg_i32 s0, 0x2200
	v_pk_fma_f32 v[24:25], v[70:71], v[18:19], v[22:23] op_sel_hi:[1,0,1]
	v_pk_fma_f32 v[18:19], v[70:71], v[18:19], v[22:23] op_sel_hi:[1,0,1] neg_lo:[0,0,1] neg_hi:[0,0,1]
	v_cvt_pk_bf16_f32 v22, v18, v25
	ds_write2_b32 v26, v21, v22 offset0:136 offset1:204
	v_pk_mul_f32 v[22:23], v[16:17], v[24:25] op_sel:[0,1]
	v_add_u32_e32 v26, 0x400, v26
	v_pk_fma_f32 v[24:25], v[70:71], v[18:19], v[22:23] op_sel_hi:[1,0,1]
	v_pk_fma_f32 v[18:19], v[70:71], v[18:19], v[22:23] op_sel_hi:[1,0,1] neg_lo:[0,0,1] neg_hi:[0,0,1]
	v_cvt_pk_bf16_f32 v21, v18, v25
	v_pk_mul_f32 v[22:23], v[16:17], v[24:25] op_sel:[0,1]
	s_nop 0
	v_pk_fma_f32 v[24:25], v[70:71], v[18:19], v[22:23] op_sel_hi:[1,0,1]
	v_pk_fma_f32 v[18:19], v[70:71], v[18:19], v[22:23] op_sel_hi:[1,0,1] neg_lo:[0,0,1] neg_hi:[0,0,1]
	v_cvt_pk_bf16_f32 v22, v18, v25
	ds_write2_b32 v26, v21, v22 offset0:16 offset1:84
	v_pk_mul_f32 v[22:23], v[16:17], v[24:25] op_sel:[0,1]
	s_nop 0
	v_pk_fma_f32 v[24:25], v[70:71], v[18:19], v[22:23] op_sel_hi:[1,0,1]
	v_pk_fma_f32 v[22:23], v[70:71], v[18:19], v[22:23] op_sel_hi:[1,0,1] neg_lo:[0,0,1] neg_hi:[0,0,1]
	v_bfe_u32 v19, v25, 16, 1
	v_bfe_u32 v18, v22, 16, 1
	v_add3_u32 v18, v22, v18, s89
	v_lshrrev_b32_e32 v18, 16, v18
	v_add3_u32 v19, v25, v19, s89
	v_pk_mul_f32 v[24:25], v[16:17], v[24:25] op_sel:[0,1]
	v_and_or_b32 v21, v19, s75, v18
	v_pk_fma_f32 v[18:19], v[70:71], v[22:23], v[24:25] op_sel_hi:[1,0,1]
	v_pk_fma_f32 v[74:75], v[70:71], v[22:23], v[24:25] op_sel_hi:[1,0,1] neg_lo:[0,0,1] neg_hi:[0,0,1]
	v_cvt_pk_bf16_f32 v18, v74, v19
	ds_write2_b32 v26, v21, v18 offset0:152 offset1:220
	v_mov_b32_e32 v18, v19
	s_cbranch_scc1 .LBB0_1156
	v_add3_u32 v16, v20, v139, s95
	v_ashrrev_i32_e32 v17, 31, v16
	v_lshlrev_b64 v[16:17], 8, v[16:17]
	v_lshl_add_u64 v[16:17], v[72:73], 0, v[16:17]
	global_load_dwordx4 v[28:31], v[16:17], off
	global_load_dwordx4 v[24:27], v[16:17], off offset:64
	global_load_dwordx4 v[20:23], v[16:17], off offset:128
	s_nop 0
	global_load_dwordx4 v[16:19], v[16:17], off offset:192
	ds_read_b128 v[56:59], v131
	ds_read_b128 v[32:35], v131 offset:64
	ds_read_b128 v[60:63], v131 offset:4352
	ds_read_b128 v[40:43], v131 offset:4416
	ds_read_b128 v[44:47], v131 offset:128
	ds_read_b128 v[36:39], v131 offset:192
	ds_read_b128 v[52:55], v131 offset:4480
	ds_read_b128 v[48:51], v131 offset:4544
	v_pk_mov_b32 v[70:71], v[66:67], v[66:67] op_sel:[1,0]
	s_movk_i32 s0, 0x1980
	v_mov_b32_e32 v72, v69
.LBB0_1158:
	v_pk_mul_f32 v[72:73], v[70:71], v[72:73] op_sel_hi:[1,0]
	v_add_u32_e32 v99, s0, v65
	v_pk_fma_f32 v[74:75], v[66:67], v[68:69], v[72:73] op_sel_hi:[1,0,1]
	v_pk_fma_f32 v[68:69], v[66:67], v[68:69], v[72:73] op_sel_hi:[1,0,1] neg_lo:[0,0,1] neg_hi:[0,0,1]
	v_cvt_pk_bf16_f32 v98, v68, v75
	v_pk_mul_f32 v[72:73], v[70:71], v[74:75] op_sel:[0,1]
	v_add_u32_e32 v100, 0x400, v99
	v_pk_fma_f32 v[74:75], v[66:67], v[68:69], v[72:73] op_sel_hi:[1,0,1]
	v_pk_fma_f32 v[68:69], v[66:67], v[68:69], v[72:73] op_sel_hi:[1,0,1] neg_lo:[0,0,1] neg_hi:[0,0,1]
	v_cvt_pk_bf16_f32 v72, v68, v75
	ds_write2_b32 v100, v72, v98 offset0:152 offset1:220
	v_pk_mul_f32 v[72:73], v[70:71], v[74:75] op_sel:[0,1]
	s_addk_i32 s0, 0xf780
	v_pk_fma_f32 v[74:75], v[66:67], v[68:69], v[72:73] op_sel_hi:[1,0,1]
	v_pk_fma_f32 v[68:69], v[66:67], v[68:69], v[72:73] op_sel_hi:[1,0,1] neg_lo:[0,0,1] neg_hi:[0,0,1]
	v_cvt_pk_bf16_f32 v98, v68, v75
	v_pk_mul_f32 v[72:73], v[70:71], v[74:75] op_sel:[0,1]
	s_cmpk_lg_i32 s0, 0xf780
	v_pk_fma_f32 v[74:75], v[66:67], v[68:69], v[72:73] op_sel_hi:[1,0,1]
	v_pk_fma_f32 v[68:69], v[66:67], v[68:69], v[72:73] op_sel_hi:[1,0,1] neg_lo:[0,0,1] neg_hi:[0,0,1]
	v_cvt_pk_bf16_f32 v72, v68, v75
	ds_write2_b32 v100, v72, v98 offset0:16 offset1:84
	v_pk_mul_f32 v[72:73], v[70:71], v[74:75] op_sel:[0,1]
	s_nop 0
	v_pk_fma_f32 v[74:75], v[66:67], v[68:69], v[72:73] op_sel_hi:[1,0,1]
	v_pk_fma_f32 v[68:69], v[66:67], v[68:69], v[72:73] op_sel_hi:[1,0,1] neg_lo:[0,0,1] neg_hi:[0,0,1]
	v_cvt_pk_bf16_f32 v98, v68, v75
	v_pk_mul_f32 v[72:73], v[70:71], v[74:75] op_sel:[0,1]
	s_nop 0
	v_pk_fma_f32 v[74:75], v[66:67], v[68:69], v[72:73] op_sel_hi:[1,0,1]
	v_pk_fma_f32 v[68:69], v[66:67], v[68:69], v[72:73] op_sel_hi:[1,0,1] neg_lo:[0,0,1] neg_hi:[0,0,1]
	v_cvt_pk_bf16_f32 v72, v68, v75
	ds_write2_b32 v99, v72, v98 offset0:136 offset1:204
	v_pk_mul_f32 v[72:73], v[70:71], v[74:75] op_sel:[0,1]
	s_nop 0
	v_pk_fma_f32 v[74:75], v[66:67], v[68:69], v[72:73] op_sel_hi:[1,0,1]
	v_pk_fma_f32 v[68:69], v[66:67], v[68:69], v[72:73] op_sel_hi:[1,0,1] neg_lo:[0,0,1] neg_hi:[0,0,1]
	v_bfe_u32 v73, v75, 16, 1
	v_bfe_u32 v72, v68, 16, 1
	v_add3_u32 v72, v68, v72, s89
	v_lshrrev_b32_e32 v72, 16, v72
	v_add3_u32 v73, v75, v73, s89
	v_pk_mul_f32 v[74:75], v[70:71], v[74:75] op_sel:[0,1]
	v_and_or_b32 v98, v73, s75, v72
	v_pk_fma_f32 v[72:73], v[66:67], v[68:69], v[74:75] op_sel_hi:[1,0,1]
	v_pk_fma_f32 v[68:69], v[66:67], v[68:69], v[74:75] op_sel_hi:[1,0,1] neg_lo:[0,0,1] neg_hi:[0,0,1]
	v_cvt_pk_bf16_f32 v69, v68, v73
	v_mov_b32_e32 v72, v73
	ds_write2_b32 v99, v69, v98 offset1:68
	s_cbranch_scc1 .LBB0_1158
	s_waitcnt vmcnt(7) lgkmcnt(11)
	v_mfma_f32_16x16x32_bf16 v[56:59], v[56:59], v[12:15], 0
	v_add_f32_e32 v65, v114, v115
	v_add_f32_e32 v69, v84, v85
	s_waitcnt lgkmcnt(9)
	v_mfma_f32_16x16x32_bf16 v[12:15], v[60:63], v[12:15], 0
	v_add_f32_e32 v67, v86, v87
	v_add_f32_e32 v70, v88, v89
	v_add_f32_e32 v66, v90, v91
	s_waitcnt vmcnt(6)
	v_mfma_f32_16x16x32_bf16 v[32:35], v[32:35], v[8:11], v[56:59]
	v_add_f32_e32 v71, v92, v93
	v_add_f32_e32 v68, v94, v95
	v_add_f32_e32 v72, v96, v97
	s_waitcnt lgkmcnt(8)
	v_mfma_f32_16x16x32_bf16 v[8:11], v[40:43], v[8:11], v[12:15]
	v_and_b32_e32 v40, 31, v137
	v_lshrrev_b32_e32 v42, 5, v138
	s_mov_b64 s[0:1], 0
	s_waitcnt vmcnt(5) lgkmcnt(7)
	v_mfma_f32_16x16x32_bf16 v[12:15], v[44:47], v[4:7], v[32:35]
	s_waitcnt lgkmcnt(5)
	v_mfma_f32_16x16x32_bf16 v[4:7], v[52:55], v[4:7], v[8:11]
	s_nop 0
	v_and_b32_e32 v34, 0xffffffdf, v137
	v_or_b32_e32 v32, 32, v137
	v_ashrrev_i32_e32 v35, 31, v34
	s_waitcnt vmcnt(4)
	v_mfma_f32_16x16x32_bf16 v[8:11], v[36:39], v[0:3], v[12:15]
	v_ashrrev_i32_e32 v33, 31, v32
	s_waitcnt lgkmcnt(4)
	v_mfma_f32_16x16x32_bf16 v[0:3], v[48:51], v[0:3], v[4:7]
	s_nop 2
	ds_read_b128 v[4:7], v131
	s_waitcnt vmcnt(3) lgkmcnt(0)
	v_mfma_f32_16x16x32_bf16 v[4:7], v[4:7], v[28:31], v[8:11]
	s_nop 2
	ds_read_b128 v[8:11], v131 offset:4352
	s_waitcnt lgkmcnt(0)
	v_mfma_f32_16x16x32_bf16 v[0:3], v[8:11], v[28:31], v[0:3]
	ds_read_b128 v[8:11], v131 offset:64
	s_waitcnt vmcnt(2) lgkmcnt(0)
	v_mfma_f32_16x16x32_bf16 v[4:7], v[8:11], v[24:27], v[4:7]
	ds_read_b128 v[8:11], v131 offset:4416
	s_waitcnt lgkmcnt(0)
	v_mfma_f32_16x16x32_bf16 v[0:3], v[8:11], v[24:27], v[0:3]
	ds_read_b128 v[8:11], v131 offset:128
	s_waitcnt vmcnt(1) lgkmcnt(0)
	v_mfma_f32_16x16x32_bf16 v[4:7], v[8:11], v[20:23], v[4:7]
	ds_read_b128 v[8:11], v131 offset:4480
	s_waitcnt lgkmcnt(0)
	v_mfma_f32_16x16x32_bf16 v[0:3], v[8:11], v[20:23], v[0:3]
	ds_read_b128 v[8:11], v131 offset:192
	s_waitcnt vmcnt(0) lgkmcnt(0)
	v_mfma_f32_16x16x32_bf16 v[4:7], v[8:11], v[16:19], v[4:7]
	ds_read_b128 v[8:11], v131 offset:4544
	s_nop 6
	v_add_f32_e32 v4, v65, v4
	v_fmac_f32_e32 v4, v113, v77
	s_waitcnt lgkmcnt(0)
	v_mfma_f32_16x16x32_bf16 v[0:3], v[8:11], v[16:19], v[0:3]
	v_mul_f32_e32 v9, 0x3d372713, v4
	v_mul_f32_e32 v9, v4, v9
	v_fma_f32 v9, v4, v9, v4
	v_mul_f32_e32 v9, 0xbfcc422a, v9
	v_mul_f32_e32 v9, 0x3fb8aa3b, v9
	v_exp_f32_e32 v9, v9
	v_lshlrev_b32_e32 v8, 1, v112
	v_add3_u32 v8, v130, v8, v132
	v_add_f32_e32 v0, v66, v0
	v_add_f32_e32 v9, 1.0, v9
	v_rcp_f32_e32 v9, v9
	v_fmac_f32_e32 v0, v80, v77
	v_mul_f32_e32 v4, v4, v9
	v_bfe_u32 v9, v4, 16, 1
	v_add3_u32 v4, v4, v9, s89
	ds_write_b16_d16_hi v8, v4 offset:34816
	v_add_f32_e32 v4, v69, v5
	v_fmac_f32_e32 v4, v83, v77
	v_mul_f32_e32 v5, 0x3d372713, v4
	v_mul_f32_e32 v5, v4, v5
	v_fma_f32 v5, v4, v5, v4
	v_mul_f32_e32 v5, 0xbfcc422a, v5
	v_mul_f32_e32 v5, 0x3fb8aa3b, v5
	v_exp_f32_e32 v5, v5
	s_nop 0
	v_add_f32_e32 v5, 1.0, v5
	v_rcp_f32_e32 v5, v5
	s_nop 0
	v_mul_f32_e32 v4, v4, v5
	v_bfe_u32 v5, v4, 16, 1
	v_add3_u32 v4, v4, v5, s89
	ds_write_b16_d16_hi v8, v4 offset:35344
	v_add_f32_e32 v4, v67, v6
	v_fmac_f32_e32 v4, v82, v77
	v_mul_f32_e32 v5, 0x3d372713, v4
	v_mul_f32_e32 v5, v4, v5
	v_fma_f32 v5, v4, v5, v4
	v_mul_f32_e32 v5, 0xbfcc422a, v5
	v_mul_f32_e32 v5, 0x3fb8aa3b, v5
	v_exp_f32_e32 v5, v5
	v_mul_u32_u24_e32 v6, 0x210, v40
	v_add_f32_e32 v5, 1.0, v5
	v_rcp_f32_e32 v5, v5
	s_nop 0
	v_mul_f32_e32 v4, v4, v5
	v_bfe_u32 v5, v4, 16, 1
	v_add3_u32 v4, v4, v5, s89
	ds_write_b16_d16_hi v8, v4 offset:35872
	v_add_f32_e32 v4, v70, v7
	v_fmac_f32_e32 v4, v81, v77
	v_mul_f32_e32 v5, 0x3d372713, v4
	v_mul_f32_e32 v5, v4, v5
	v_fma_f32 v5, v4, v5, v4
	v_mul_f32_e32 v5, 0xbfcc422a, v5
	v_mul_f32_e32 v5, 0x3fb8aa3b, v5
	v_exp_f32_e32 v5, v5
	v_lshlrev_b32_e32 v7, 4, v42
	v_add3_u32 v41, v6, v7, s26
	v_lshrrev_b32_e32 v6, 1, v137
	v_add_f32_e32 v5, 1.0, v5
	v_rcp_f32_e32 v5, v5
	v_and_b32_e32 v6, 16, v6
	v_mul_f32_e32 v4, v4, v5
	v_bfe_u32 v5, v4, 16, 1
	v_add3_u32 v4, v4, v5, s89
	ds_write_b16_d16_hi v8, v4 offset:36400
	v_mul_f32_e32 v4, 0x3d372713, v0
	v_mul_f32_e32 v4, v0, v4
	v_fma_f32 v4, v0, v4, v0
	v_mul_f32_e32 v4, 0xbfcc422a, v4
	v_mul_f32_e32 v4, 0x3fb8aa3b, v4
	v_exp_f32_e32 v4, v4
	s_nop 0
	v_add_f32_e32 v4, 1.0, v4
	v_rcp_f32_e32 v4, v4
	s_nop 0
	v_mul_f32_e32 v0, v0, v4
	v_bfe_u32 v4, v0, 16, 1
	v_add3_u32 v0, v0, v4, s89
	ds_write_b16_d16_hi v8, v0 offset:43264
	v_add_f32_e32 v0, v71, v1
	v_fmac_f32_e32 v0, v79, v77
	v_mul_f32_e32 v1, 0x3d372713, v0
	v_mul_f32_e32 v1, v0, v1
	v_fma_f32 v1, v0, v1, v0
	v_mul_f32_e32 v1, 0xbfcc422a, v1
	v_mul_f32_e32 v1, 0x3fb8aa3b, v1
	v_exp_f32_e32 v1, v1
	v_lshlrev_b64 v[4:5], 9, v[32:33]
	v_or_b32_e32 v4, v4, v6
	v_add_f32_e32 v1, 1.0, v1
	v_rcp_f32_e32 v1, v1
	s_nop 0
	v_mul_f32_e32 v0, v0, v1
	v_bfe_u32 v1, v0, 16, 1
	v_add3_u32 v0, v0, v1, s89
	ds_write_b16_d16_hi v8, v0 offset:43792
	v_add_f32_e32 v0, v68, v2
	v_fmac_f32_e32 v0, v78, v77
	v_mul_f32_e32 v1, 0x3d372713, v0
	v_mul_f32_e32 v1, v0, v1
	v_fma_f32 v1, v0, v1, v0
	v_mul_f32_e32 v1, 0xbfcc422a, v1
	v_mul_f32_e32 v1, 0x3fb8aa3b, v1
	v_exp_f32_e32 v1, v1
	s_nop 0
	v_add_f32_e32 v1, 1.0, v1
	v_rcp_f32_e32 v1, v1
	s_nop 0
	v_mul_f32_e32 v0, v0, v1
	v_bfe_u32 v1, v0, 16, 1
	v_add3_u32 v0, v0, v1, s89
	ds_write_b16_d16_hi v8, v0 offset:44320
	v_add_f32_e32 v0, v72, v3
	v_fmac_f32_e32 v0, v76, v77
	v_mul_f32_e32 v1, 0x3d372713, v0
	v_mul_f32_e32 v1, v0, v1
	v_fma_f32 v1, v0, v1, v0
	v_mul_f32_e32 v1, 0xbfcc422a, v1
	v_mul_f32_e32 v1, 0x3fb8aa3b, v1
	v_exp_f32_e32 v1, v1
	v_lshlrev_b64 v[2:3], 9, v[34:35]
	v_or_b32_e32 v2, v2, v6
	v_add_f32_e32 v1, 1.0, v1
	v_rcp_f32_e32 v1, v1
	s_nop 0
	v_mul_f32_e32 v0, v0, v1
	v_bfe_u32 v1, v0, 16, 1
	v_add3_u32 v0, v0, v1, s89
	ds_write_b16_d16_hi v8, v0 offset:44848
	s_waitcnt lgkmcnt(0)
	s_barrier
	ds_read_b64 v[0:1], v229 offset:63760
	s_waitcnt lgkmcnt(0)
	v_lshl_add_u64 v[36:37], v[0:1], 0, v[4:5]
	v_lshl_add_u64 v[38:39], v[0:1], 0, v[2:3]
	v_mov_b32_e32 v0, 0
	v_mov_b32_e32 v1, v0
	v_mov_b32_e32 v2, v0
	v_mov_b32_e32 v3, v0
	v_mov_b32_e32 v4, v0
	v_mov_b32_e32 v5, v0
	v_mov_b32_e32 v6, v0
	v_mov_b32_e32 v7, v0
	v_mov_b32_e32 v8, v0
	v_mov_b32_e32 v9, v0
	v_mov_b32_e32 v10, v0
	v_mov_b32_e32 v11, v0
	v_mov_b32_e32 v12, v0
	v_mov_b32_e32 v13, v0
	v_mov_b32_e32 v14, v0
	v_mov_b32_e32 v15, v0
	v_mov_b32_e32 v16, v0
	v_mov_b32_e32 v17, v0
	v_mov_b32_e32 v18, v0
	v_mov_b32_e32 v19, v0
	v_mov_b32_e32 v20, v0
	v_mov_b32_e32 v21, v0
	v_mov_b32_e32 v22, v0
	v_mov_b32_e32 v23, v0
	v_mov_b32_e32 v24, v0
	v_mov_b32_e32 v25, v0
	v_mov_b32_e32 v26, v0
	v_mov_b32_e32 v27, v0
	v_mov_b32_e32 v28, v0
	v_mov_b32_e32 v29, v0
	v_mov_b32_e32 v30, v0
	v_mov_b32_e32 v31, v0

.LBB0_1477:
	v_pk_mul_f32 v[134:135], v[132:133], v[134:135] op_sel_hi:[1,0]
	v_add_u32_e32 v175, s0, v65
	v_pk_fma_f32 v[172:173], v[128:129], v[130:131], v[134:135] op_sel_hi:[1,0,1]
	v_pk_fma_f32 v[130:131], v[128:129], v[130:131], v[134:135] op_sel_hi:[1,0,1] neg_lo:[0,0,1] neg_hi:[0,0,1]
	v_cvt_pk_bf16_f32 v174, v130, v173
	v_pk_mul_f32 v[134:135], v[132:133], v[172:173] op_sel:[0,1]
	v_add_u32_e32 v176, 0x400, v175
	v_pk_fma_f32 v[172:173], v[128:129], v[130:131], v[134:135] op_sel_hi:[1,0,1]
	v_pk_fma_f32 v[130:131], v[128:129], v[130:131], v[134:135] op_sel_hi:[1,0,1] neg_lo:[0,0,1] neg_hi:[0,0,1]
	v_cvt_pk_bf16_f32 v134, v130, v173
	ds_write2_b32 v176, v134, v174 offset0:152 offset1:220
	v_pk_mul_f32 v[134:135], v[132:133], v[172:173] op_sel:[0,1]
	s_addk_i32 s0, 0xf780
	v_pk_fma_f32 v[172:173], v[128:129], v[130:131], v[134:135] op_sel_hi:[1,0,1]
	v_pk_fma_f32 v[130:131], v[128:129], v[130:131], v[134:135] op_sel_hi:[1,0,1] neg_lo:[0,0,1] neg_hi:[0,0,1]
	v_cvt_pk_bf16_f32 v174, v130, v173
	v_pk_mul_f32 v[134:135], v[132:133], v[172:173] op_sel:[0,1]
	s_cmpk_lg_i32 s0, 0xf780
	v_pk_fma_f32 v[172:173], v[128:129], v[130:131], v[134:135] op_sel_hi:[1,0,1]
	v_pk_fma_f32 v[130:131], v[128:129], v[130:131], v[134:135] op_sel_hi:[1,0,1] neg_lo:[0,0,1] neg_hi:[0,0,1]
	v_cvt_pk_bf16_f32 v134, v130, v173
	ds_write2_b32 v176, v134, v174 offset0:16 offset1:84
	v_pk_mul_f32 v[134:135], v[132:133], v[172:173] op_sel:[0,1]
	s_nop 0
	v_pk_fma_f32 v[172:173], v[128:129], v[130:131], v[134:135] op_sel_hi:[1,0,1]
	v_pk_fma_f32 v[130:131], v[128:129], v[130:131], v[134:135] op_sel_hi:[1,0,1] neg_lo:[0,0,1] neg_hi:[0,0,1]
	v_cvt_pk_bf16_f32 v174, v130, v173
	v_pk_mul_f32 v[134:135], v[132:133], v[172:173] op_sel:[0,1]
	s_nop 0
	v_pk_fma_f32 v[172:173], v[128:129], v[130:131], v[134:135] op_sel_hi:[1,0,1]
	v_pk_fma_f32 v[130:131], v[128:129], v[130:131], v[134:135] op_sel_hi:[1,0,1] neg_lo:[0,0,1] neg_hi:[0,0,1]
	v_cvt_pk_bf16_f32 v134, v130, v173
	ds_write2_b32 v175, v134, v174 offset0:136 offset1:204
	v_pk_mul_f32 v[134:135], v[132:133], v[172:173] op_sel:[0,1]
	s_nop 0
	v_pk_fma_f32 v[172:173], v[128:129], v[130:131], v[134:135] op_sel_hi:[1,0,1]
	v_pk_fma_f32 v[130:131], v[128:129], v[130:131], v[134:135] op_sel_hi:[1,0,1] neg_lo:[0,0,1] neg_hi:[0,0,1]
	v_bfe_u32 v135, v173, 16, 1
	v_bfe_u32 v134, v130, 16, 1
	v_add3_u32 v134, v130, v134, s89
	v_lshrrev_b32_e32 v134, 16, v134
	v_add3_u32 v135, v173, v135, s89
	v_pk_mul_f32 v[172:173], v[132:133], v[172:173] op_sel:[0,1]
	v_and_or_b32 v174, v135, s75, v134
	v_pk_fma_f32 v[134:135], v[128:129], v[130:131], v[172:173] op_sel_hi:[1,0,1]
	v_pk_fma_f32 v[130:131], v[128:129], v[130:131], v[172:173] op_sel_hi:[1,0,1] neg_lo:[0,0,1] neg_hi:[0,0,1]
	v_cvt_pk_bf16_f32 v131, v130, v135
	v_mov_b32_e32 v134, v135
	ds_write2_b32 v175, v131, v174 offset1:68
	s_cbranch_scc1 .LBB0_1477
	s_waitcnt lgkmcnt(11)
	v_mfma_f32_16x16x32_bf16 v[60:63], v[60:63], v[12:15], 0
	v_add_u32_e32 v131, v170, v171
	v_add_f32_e32 v128, v156, v157
	s_waitcnt lgkmcnt(10)
	v_mfma_f32_16x16x32_bf16 v[56:59], v[56:59], v[8:11], v[60:63]
	v_add_f32_e32 v129, v160, v161
	v_add_f32_e32 v160, v154, v155
	v_lshlrev_b32_e32 v130, 1, v139
	s_nop 0
	ds_read_b128 v[60:63], v131
	s_waitcnt lgkmcnt(8)
	v_mfma_f32_16x16x32_bf16 v[52:55], v[52:55], v[4:7], v[56:59]
	v_add_f32_e32 v158, v158, v159
	v_lshlrev_b32_e32 v159, 1, v64
	v_add_f32_e32 v171, v164, v166
	ds_read_b128 v[56:59], v131 offset:64
	v_mfma_f32_16x16x32_bf16 v[12:15], v[44:47], v[12:15], 0
	v_add_f32_e32 v170, v162, v163
	v_add_f32_e32 v172, v165, v167
	v_add_f32_e32 v169, v168, v169
	s_waitcnt lgkmcnt(8)
	v_mfma_f32_16x16x32_bf16 v[48:51], v[48:51], v[0:3], v[52:55]
	s_mov_b32 s0, 0
	s_nop 1
	ds_read_b128 v[52:55], v131 offset:128
	v_mfma_f32_16x16x32_bf16 v[8:11], v[40:43], v[8:11], v[12:15]
	s_waitcnt vmcnt(3) lgkmcnt(2)
	v_mfma_f32_16x16x32_bf16 v[48:51], v[60:63], v[28:31], v[48:51]
	ds_read_b128 v[60:63], v131 offset:192
	v_mfma_f32_16x16x32_bf16 v[4:7], v[36:39], v[4:7], v[8:11]
	s_waitcnt vmcnt(2) lgkmcnt(2)
	v_mfma_f32_16x16x32_bf16 v[48:51], v[56:59], v[24:27], v[48:51]
	ds_read_b128 v[56:59], v131 offset:4352
	ds_read_b128 v[132:135], v131 offset:4416
	v_mfma_f32_16x16x32_bf16 v[0:3], v[32:35], v[0:3], v[4:7]
	s_waitcnt vmcnt(1) lgkmcnt(3)
	v_mfma_f32_16x16x32_bf16 v[48:51], v[52:55], v[20:23], v[48:51]
	ds_read_b128 v[52:55], v131 offset:4480
	ds_read_b128 v[154:157], v131 offset:4544
	s_waitcnt lgkmcnt(3)
	v_mfma_f32_16x16x32_bf16 v[0:3], v[56:59], v[28:31], v[0:3]
	s_waitcnt vmcnt(0)
	v_mfma_f32_16x16x32_bf16 v[48:51], v[60:63], v[16:19], v[48:51]
	s_waitcnt lgkmcnt(2)
	v_mfma_f32_16x16x32_bf16 v[0:3], v[132:135], v[24:27], v[0:3]
	v_mul_u32_u24_e32 v132, 0x840, v149
	s_nop 4
	v_add_f32_e32 v48, v128, v48
	v_fmac_f32_e32 v48, v153, v148
	v_mul_f32_e32 v60, 0x3d372713, v48
	v_mul_f32_e32 v44, v48, v60
	v_add_f32_e32 v13, v160, v49
	s_waitcnt lgkmcnt(1)
	v_mfma_f32_16x16x32_bf16 v[0:3], v[52:55], v[20:23], v[0:3]
	v_fma_f32 v44, v48, v44, v48
	v_fmac_f32_e32 v13, v152, v148
	v_mul_f32_e32 v44, 0xbfcc422a, v44
	v_mul_f32_e32 v9, 0x3d372713, v13
	v_add_f32_e32 v21, v129, v50
	v_mul_f32_e32 v44, 0x3fb8aa3b, v44
	v_mul_f32_e32 v4, v13, v9
	v_fmac_f32_e32 v21, v151, v148
	v_exp_f32_e32 v12, v44
	v_fma_f32 v4, v13, v4, v13
	s_waitcnt lgkmcnt(0)
	v_mfma_f32_16x16x32_bf16 v[16:19], v[154:157], v[16:19], v[0:3]
	v_mul_f32_e32 v4, 0xbfcc422a, v4
	v_mul_f32_e32 v4, 0x3fb8aa3b, v4
	v_exp_f32_e32 v4, v4
	v_mul_f32_e32 v0, 0x3d372713, v21
	v_mul_f32_e32 v0, v21, v0
	v_fma_f32 v0, v21, v0, v21
	v_mul_f32_e32 v0, 0xbfcc422a, v0
	v_add_f32_e32 v8, 1.0, v12
	v_mul_f32_e32 v0, 0x3fb8aa3b, v0
	v_rcp_f32_e32 v8, v8
	v_exp_f32_e32 v0, v0
	v_add_f32_e32 v4, 1.0, v4
	v_rcp_f32_e32 v4, v4
	v_lshlrev_b32_e32 v128, 4, v143
	v_mul_f32_e32 v5, v48, v8
	v_add_f32_e32 v0, 1.0, v0
	v_ashrrev_i32_e32 v129, 31, v128
	v_bfe_u32 v6, v5, 16, 1
	v_rcp_f32_e32 v25, v0
	v_lshlrev_b64 v[0:1], 2, v[128:129]
	v_add3_u32 v5, v5, v6, s89
	v_add3_u32 v24, v130, v159, v132
	v_lshl_add_u64 v[2:3], v[76:77], 0, v[0:1]
	ds_write_b16_d16_hi v24, v5 offset:34816
	v_mul_f32_e32 v22, v13, v4
	v_lshl_add_u64 v[4:5], v[2:3], 0, v[80:81]
	v_lshl_add_u64 v[0:1], v[78:79], 0, v[0:1]
	v_add_co_u32_e32 v6, vcc, s92, v4
	v_add_f32_e32 v26, v158, v51
	s_nop 0
	v_addc_co_u32_e32 v7, vcc, 0, v5, vcc
	global_load_dword v157, v[4:5], off
	global_load_dword v158, v[6:7], off
	v_lshl_add_u64 v[4:5], v[0:1], 0, v[82:83]
	global_load_dword v151, v[4:5], off
	v_lshl_add_u64 v[4:5], v[2:3], 0, v[84:85]
	v_add_co_u32_e32 v6, vcc, s92, v4
	v_fmac_f32_e32 v26, v150, v148
	s_nop 0
	v_addc_co_u32_e32 v7, vcc, 0, v5, vcc
	global_load_dword v153, v[4:5], off
	global_load_dword v154, v[6:7], off
	v_lshl_add_u64 v[4:5], v[0:1], 0, v[86:87]
	global_load_dword v152, v[4:5], off
	v_lshl_add_u64 v[4:5], v[2:3], 0, v[88:89]
	v_add_co_u32_e32 v6, vcc, s92, v4
	v_add_u32_e32 v20, s6, v128
	s_nop 0
	v_addc_co_u32_e32 v7, vcc, 0, v5, vcc
	global_load_dword v159, v[4:5], off
	global_load_dword v160, v[6:7], off
	v_lshl_add_u64 v[4:5], v[0:1], 0, v[90:91]
	global_load_dword v150, v[4:5], off
	v_lshl_add_u64 v[4:5], v[2:3], 0, v[92:93]
	v_add_co_u32_e32 v6, vcc, s92, v4
	v_mul_f32_e32 v27, 0x3d372713, v26
	s_nop 0
	v_addc_co_u32_e32 v7, vcc, 0, v5, vcc
	global_load_dword v155, v[4:5], off
	global_load_dword v156, v[6:7], off
	v_lshl_add_u64 v[4:5], v[0:1], 0, v[94:95]
	global_load_dword v149, v[4:5], off
	v_lshl_add_u64 v[4:5], v[2:3], 0, v[96:97]
	v_add_co_u32_e32 v6, vcc, s92, v4
	v_mul_f32_e32 v27, v26, v27
	s_nop 0
	v_addc_co_u32_e32 v7, vcc, 0, v5, vcc
	global_load_dword v164, v[4:5], off
	global_load_dword v166, v[6:7], off
	v_lshl_add_u64 v[4:5], v[0:1], 0, v[98:99]
	global_load_dword v135, v[4:5], off
	v_lshl_add_u64 v[4:5], v[2:3], 0, v[100:101]
	v_add_co_u32_e32 v6, vcc, s92, v4
	v_fma_f32 v27, v26, v27, v26
	s_nop 0
	v_addc_co_u32_e32 v7, vcc, 0, v5, vcc
	global_load_dword v161, v[4:5], off
	global_load_dword v162, v[6:7], off
	v_lshl_add_u64 v[4:5], v[0:1], 0, v[102:103]
	global_load_dword v134, v[4:5], off
	v_lshl_add_u64 v[4:5], v[2:3], 0, v[104:105]
	v_add_co_u32_e32 v6, vcc, s92, v4
	v_lshl_add_u64 v[2:3], v[2:3], 0, v[110:111]
	s_nop 0
	v_addc_co_u32_e32 v7, vcc, 0, v5, vcc
	global_load_dword v167, v[4:5], off
	global_load_dword v168, v[6:7], off
	v_lshl_add_u64 v[4:5], v[0:1], 0, v[106:107]
	global_load_dword v129, v[4:5], off
	v_add_co_u32_e32 v4, vcc, s92, v2
	v_lshl_add_u64 v[0:1], v[0:1], 0, v[108:109]
	s_nop 0
	v_addc_co_u32_e32 v5, vcc, 0, v3, vcc
	global_load_dword v163, v[2:3], off
	global_load_dword v165, v[4:5], off
	ds_read_b64 v[2:3], v229 offset:63640
	global_load_dword v133, v[0:1], off
	v_add_u32_e32 v0, v128, v140
	v_ashrrev_i32_e32 v1, 31, v0
	v_mul_f32_e32 v27, 0xbfcc422a, v27
	s_waitcnt lgkmcnt(0)
	v_lshl_add_u64 v[0:1], v[0:1], 2, v[2:3]
	global_load_dword v143, v[0:1], off
	v_or_b32_e32 v0, v20, v139
	v_ashrrev_i32_e32 v1, 31, v0
	v_lshlrev_b64 v[0:1], 8, v[0:1]
	v_lshl_add_u64 v[0:1], v[72:73], 0, v[0:1]
	global_load_dwordx4 v[12:15], v[0:1], off
	global_load_dwordx4 v[8:11], v[0:1], off offset:64
	global_load_dwordx4 v[4:7], v[0:1], off offset:128
	s_nop 0
	global_load_dwordx4 v[0:3], v[0:1], off offset:192
	v_mul_f32_e32 v27, 0x3fb8aa3b, v27
	v_exp_f32_e32 v27, v27
	v_bfe_u32 v23, v22, 16, 1
	v_add3_u32 v22, v22, v23, s89
	ds_write_b16_d16_hi v24, v22 offset:35344
	v_add_f32_e32 v22, 1.0, v27
	v_rcp_f32_e32 v22, v22
	v_mul_f32_e32 v21, v21, v25
	v_bfe_u32 v23, v21, 16, 1
	v_add_f32_e32 v16, v172, v16
	v_add3_u32 v21, v21, v23, s89
	v_fmac_f32_e32 v16, v144, v148
	ds_write_b16_d16_hi v24, v21 offset:35872
	v_mul_f32_e32 v21, v26, v22
	v_mul_f32_e32 v22, 0x3d372713, v16
	v_mul_f32_e32 v22, v16, v22
	v_fma_f32 v22, v16, v22, v16
	v_mul_f32_e32 v22, 0xbfcc422a, v22
	v_mul_f32_e32 v22, 0x3fb8aa3b, v22
	v_exp_f32_e32 v22, v22
	v_bfe_u32 v23, v21, 16, 1
	v_add_f32_e32 v17, v170, v17
	v_add3_u32 v21, v21, v23, s89
	v_fmac_f32_e32 v17, v145, v148
	ds_write_b16_d16_hi v24, v21 offset:36400
	v_add_f32_e32 v21, 1.0, v22
	v_mul_f32_e32 v22, 0x3d372713, v17
	v_mul_f32_e32 v22, v17, v22
	v_fma_f32 v22, v17, v22, v17
	v_rcp_f32_e32 v21, v21
	v_mul_f32_e32 v22, 0xbfcc422a, v22
	v_mul_f32_e32 v22, 0x3fb8aa3b, v22
	v_exp_f32_e32 v22, v22
	v_mul_f32_e32 v16, v16, v21
	v_add_f32_e32 v18, v169, v18
	v_bfe_u32 v21, v16, 16, 1
	v_fmac_f32_e32 v18, v146, v148
	v_add3_u32 v16, v16, v21, s89
	v_add_f32_e32 v21, 1.0, v22
	v_mul_f32_e32 v22, 0x3d372713, v18
	v_mul_f32_e32 v22, v18, v22
	v_fma_f32 v22, v18, v22, v18
	v_mul_f32_e32 v22, 0xbfcc422a, v22
	v_mul_f32_e32 v22, 0x3fb8aa3b, v22
	v_rcp_f32_e32 v21, v21
	v_exp_f32_e32 v22, v22
	v_add_f32_e32 v19, v171, v19
	v_fmac_f32_e32 v19, v147, v148
	ds_write_b16_d16_hi v24, v16 offset:43264
	v_mul_f32_e32 v16, v17, v21
	v_add_f32_e32 v21, 1.0, v22
	v_mul_f32_e32 v22, 0x3d372713, v19
	v_mul_f32_e32 v22, v19, v22
	v_fma_f32 v22, v19, v22, v19
	v_mul_f32_e32 v22, 0xbfcc422a, v22
	v_mul_f32_e32 v22, 0x3fb8aa3b, v22
	v_exp_f32_e32 v22, v22
	v_rcp_f32_e32 v21, v21
	v_bfe_u32 v17, v16, 16, 1
	v_add3_u32 v16, v16, v17, s89
	v_add_f32_e32 v17, 1.0, v22
	v_rcp_f32_e32 v17, v17
	ds_write_b16_d16_hi v24, v16 offset:43792
	v_mul_f32_e32 v16, v18, v21
	v_bfe_u32 v18, v16, 16, 1
	v_add3_u32 v16, v16, v18, s89
	ds_write_b16_d16_hi v24, v16 offset:44320
	v_mul_f32_e32 v16, v19, v17
	v_bfe_u32 v17, v16, 16, 1
	v_add3_u32 v16, v16, v17, s89
	ds_write_b16_d16_hi v24, v16 offset:44848
	v_pk_mov_b32 v[16:17], v[124:125], v[124:125] op_sel:[1,0]
	v_mov_b32_e32 v18, v127

.LBB0_1481:
	v_pk_mul_f32 v[126:127], v[124:125], v[126:127] op_sel_hi:[1,0]
	v_add_u32_e32 v147, s0, v65
	v_pk_fma_f32 v[144:145], v[120:121], v[122:123], v[126:127] op_sel_hi:[1,0,1]
	v_pk_fma_f32 v[122:123], v[120:121], v[122:123], v[126:127] op_sel_hi:[1,0,1] neg_lo:[0,0,1] neg_hi:[0,0,1]
	v_cvt_pk_bf16_f32 v146, v122, v145
	v_pk_mul_f32 v[126:127], v[124:125], v[144:145] op_sel:[0,1]
	v_add_u32_e32 v148, 0x400, v147
	v_pk_fma_f32 v[144:145], v[120:121], v[122:123], v[126:127] op_sel_hi:[1,0,1]
	v_pk_fma_f32 v[122:123], v[120:121], v[122:123], v[126:127] op_sel_hi:[1,0,1] neg_lo:[0,0,1] neg_hi:[0,0,1]
	v_cvt_pk_bf16_f32 v126, v122, v145
	ds_write2_b32 v148, v126, v146 offset0:152 offset1:220
	v_pk_mul_f32 v[126:127], v[124:125], v[144:145] op_sel:[0,1]
	s_addk_i32 s0, 0xf780
	v_pk_fma_f32 v[144:145], v[120:121], v[122:123], v[126:127] op_sel_hi:[1,0,1]
	v_pk_fma_f32 v[122:123], v[120:121], v[122:123], v[126:127] op_sel_hi:[1,0,1] neg_lo:[0,0,1] neg_hi:[0,0,1]
	v_cvt_pk_bf16_f32 v146, v122, v145
	v_pk_mul_f32 v[126:127], v[124:125], v[144:145] op_sel:[0,1]
	s_cmpk_lg_i32 s0, 0xf780
	v_pk_fma_f32 v[144:145], v[120:121], v[122:123], v[126:127] op_sel_hi:[1,0,1]
	v_pk_fma_f32 v[122:123], v[120:121], v[122:123], v[126:127] op_sel_hi:[1,0,1] neg_lo:[0,0,1] neg_hi:[0,0,1]
	v_cvt_pk_bf16_f32 v126, v122, v145
	ds_write2_b32 v148, v126, v146 offset0:16 offset1:84
	v_pk_mul_f32 v[126:127], v[124:125], v[144:145] op_sel:[0,1]
	s_nop 0
	v_pk_fma_f32 v[144:145], v[120:121], v[122:123], v[126:127] op_sel_hi:[1,0,1]
	v_pk_fma_f32 v[122:123], v[120:121], v[122:123], v[126:127] op_sel_hi:[1,0,1] neg_lo:[0,0,1] neg_hi:[0,0,1]
	v_cvt_pk_bf16_f32 v146, v122, v145
	v_pk_mul_f32 v[126:127], v[124:125], v[144:145] op_sel:[0,1]
	s_nop 0
	v_pk_fma_f32 v[144:145], v[120:121], v[122:123], v[126:127] op_sel_hi:[1,0,1]
	v_pk_fma_f32 v[122:123], v[120:121], v[122:123], v[126:127] op_sel_hi:[1,0,1] neg_lo:[0,0,1] neg_hi:[0,0,1]
	v_cvt_pk_bf16_f32 v126, v122, v145
	ds_write2_b32 v147, v126, v146 offset0:136 offset1:204
	v_pk_mul_f32 v[126:127], v[124:125], v[144:145] op_sel:[0,1]
	s_nop 0
	v_pk_fma_f32 v[144:145], v[120:121], v[122:123], v[126:127] op_sel_hi:[1,0,1]
	v_pk_fma_f32 v[122:123], v[120:121], v[122:123], v[126:127] op_sel_hi:[1,0,1] neg_lo:[0,0,1] neg_hi:[0,0,1]
	v_bfe_u32 v127, v145, 16, 1
	v_bfe_u32 v126, v122, 16, 1
	v_add3_u32 v126, v122, v126, s89
	v_lshrrev_b32_e32 v126, 16, v126
	v_add3_u32 v127, v145, v127, s89
	v_pk_mul_f32 v[144:145], v[124:125], v[144:145] op_sel:[0,1]
	v_and_or_b32 v146, v127, s75, v126
	v_pk_fma_f32 v[126:127], v[120:121], v[122:123], v[144:145] op_sel_hi:[1,0,1]
	v_pk_fma_f32 v[122:123], v[120:121], v[122:123], v[144:145] op_sel_hi:[1,0,1] neg_lo:[0,0,1] neg_hi:[0,0,1]
	v_cvt_pk_bf16_f32 v123, v122, v127
	v_mov_b32_e32 v126, v127
	ds_write2_b32 v147, v123, v146 offset1:68
	s_cbranch_scc1 .LBB0_1481
	s_waitcnt vmcnt(7) lgkmcnt(11)
	v_mfma_f32_16x16x32_bf16 v[56:59], v[56:59], v[12:15], 0
	v_add_f32_e32 v144, v157, v158
	v_add_f32_e32 v146, v153, v154
	s_waitcnt vmcnt(6) lgkmcnt(10)
	v_mfma_f32_16x16x32_bf16 v[56:59], v[60:63], v[8:11], v[56:59]
	ds_read_b128 v[60:63], v131
	v_add_f32_e32 v145, v159, v160
	v_lshlrev_b32_e32 v128, 1, v128
	s_waitcnt vmcnt(5) lgkmcnt(8)
	v_mfma_f32_16x16x32_bf16 v[52:55], v[52:55], v[4:7], v[56:59]
	v_add_f32_e32 v147, v155, v156
	v_add_f32_e32 v164, v164, v166
	v_add_f32_e32 v161, v161, v162
	ds_read_b128 v[56:59], v131 offset:64
	s_waitcnt vmcnt(4) lgkmcnt(8)
	v_mfma_f32_16x16x32_bf16 v[48:51], v[48:51], v[0:3], v[52:55]
	v_add_f32_e32 v160, v167, v168
	v_add_f32_e32 v162, v163, v165
	s_mov_b32 s0, 0
	ds_read_b128 v[52:55], v131 offset:128
	s_waitcnt vmcnt(3) lgkmcnt(2)
	v_mfma_f32_16x16x32_bf16 v[48:51], v[60:63], v[28:31], v[48:51]
	ds_read_b128 v[60:63], v131 offset:192
	s_waitcnt vmcnt(2) lgkmcnt(2)
	v_mfma_f32_16x16x32_bf16 v[48:51], v[56:59], v[24:27], v[48:51]
	ds_read_b128 v[56:59], v131 offset:4352
	ds_read_b128 v[120:123], v131 offset:4416
	s_waitcnt vmcnt(1) lgkmcnt(3)
	v_mfma_f32_16x16x32_bf16 v[48:51], v[52:55], v[20:23], v[48:51]
	ds_read_b128 v[52:55], v131 offset:4480
	ds_read_b128 v[124:127], v131 offset:4544
	v_mfma_f32_16x16x32_bf16 v[12:15], v[44:47], v[12:15], 0
	s_waitcnt vmcnt(0) lgkmcnt(4)
	v_mfma_f32_16x16x32_bf16 v[48:51], v[60:63], v[16:19], v[48:51]
	v_mfma_f32_16x16x32_bf16 v[8:11], v[40:43], v[8:11], v[12:15]
	v_mfma_f32_16x16x32_bf16 v[4:7], v[36:39], v[4:7], v[8:11]
	s_nop 5
	v_add_f32_e32 v48, v144, v48
	v_fmac_f32_e32 v48, v151, v143
	v_mul_f32_e32 v60, 0x3d372713, v48
	v_mul_f32_e32 v44, v48, v60
	v_fma_f32 v44, v48, v44, v48
	v_mfma_f32_16x16x32_bf16 v[0:3], v[32:35], v[0:3], v[4:7]
	v_mul_f32_e32 v44, 0xbfcc422a, v44
	v_mul_f32_e32 v44, 0x3fb8aa3b, v44
	v_exp_f32_e32 v12, v44
	s_waitcnt lgkmcnt(3)
	v_mfma_f32_16x16x32_bf16 v[0:3], v[56:59], v[28:31], v[0:3]
	v_add_f32_e32 v49, v146, v49
	v_fmac_f32_e32 v49, v152, v143
	v_add_f32_e32 v8, 1.0, v12
	v_rcp_f32_e32 v8, v8
	s_waitcnt lgkmcnt(2)
	v_mfma_f32_16x16x32_bf16 v[0:3], v[120:123], v[24:27], v[0:3]
	v_mul_f32_e32 v61, 0x3d372713, v49
	v_add_f32_e32 v24, v145, v50
	v_mul_f32_e32 v5, v48, v8
	s_waitcnt lgkmcnt(1)
	v_mfma_f32_16x16x32_bf16 v[0:3], v[52:55], v[20:23], v[0:3]
	v_mul_f32_e32 v13, v49, v61
	v_bfe_u32 v6, v5, 16, 1
	v_fmac_f32_e32 v24, v150, v143
	v_fma_f32 v13, v49, v13, v49
	v_add3_u32 v5, v5, v6, s89
	v_mul_f32_e32 v6, 0x3d372713, v24
	v_mul_f32_e32 v9, 0xbfcc422a, v13
	v_mul_f32_e32 v6, v24, v6
	v_mul_f32_e32 v4, 0x3fb8aa3b, v9
	s_waitcnt lgkmcnt(0)
	v_mfma_f32_16x16x32_bf16 v[16:19], v[124:127], v[16:19], v[0:3]
	v_exp_f32_e32 v4, v4
	v_lshlrev_b32_e32 v120, 4, v142
	v_ashrrev_i32_e32 v121, 31, v120
	v_fma_f32 v0, v24, v6, v24
	v_mul_f32_e32 v0, 0xbfcc422a, v0
	v_mul_f32_e32 v0, 0x3fb8aa3b, v0
	v_exp_f32_e32 v0, v0
	v_add_f32_e32 v4, 1.0, v4
	v_rcp_f32_e32 v4, v4
	v_add3_u32 v28, v130, v128, v132
	v_add_f32_e32 v0, 1.0, v0
	v_rcp_f32_e32 v23, v0
	v_lshlrev_b64 v[0:1], 2, v[120:121]
	v_lshl_add_u64 v[2:3], v[76:77], 0, v[0:1]
	ds_write_b16_d16_hi v28, v5 offset:34816
	v_mul_f32_e32 v21, v49, v4
	v_lshl_add_u64 v[4:5], v[2:3], 0, v[80:81]
	v_add_f32_e32 v25, v147, v51
	v_lshl_add_u64 v[0:1], v[78:79], 0, v[0:1]
	v_add_co_u32_e32 v6, vcc, s92, v4
	v_fmac_f32_e32 v25, v149, v143
	s_nop 0
	v_addc_co_u32_e32 v7, vcc, 0, v5, vcc
	global_load_dword v148, v[4:5], off
	global_load_dword v149, v[6:7], off
	v_lshl_add_u64 v[4:5], v[0:1], 0, v[82:83]
	global_load_dword v128, v[4:5], off
	v_lshl_add_u64 v[4:5], v[2:3], 0, v[84:85]
	v_add_co_u32_e32 v6, vcc, s92, v4
	v_add_u32_e32 v20, s6, v120
	s_nop 0
	v_addc_co_u32_e32 v7, vcc, 0, v5, vcc
	global_load_dword v144, v[4:5], off
	global_load_dword v145, v[6:7], off
	v_lshl_add_u64 v[4:5], v[0:1], 0, v[86:87]
	global_load_dword v142, v[4:5], off
	v_lshl_add_u64 v[4:5], v[2:3], 0, v[88:89]
	v_add_co_u32_e32 v6, vcc, s92, v4
	v_mul_f32_e32 v26, 0x3d372713, v25
	s_nop 0
	v_addc_co_u32_e32 v7, vcc, 0, v5, vcc
	global_load_dword v150, v[4:5], off
	global_load_dword v151, v[6:7], off
	v_lshl_add_u64 v[4:5], v[0:1], 0, v[90:91]
	global_load_dword v127, v[4:5], off
	v_lshl_add_u64 v[4:5], v[2:3], 0, v[92:93]
	v_add_co_u32_e32 v6, vcc, s92, v4
	v_mul_f32_e32 v26, v25, v26
	s_nop 0
	v_addc_co_u32_e32 v7, vcc, 0, v5, vcc
	global_load_dword v146, v[4:5], off
	global_load_dword v147, v[6:7], off
	v_lshl_add_u64 v[4:5], v[0:1], 0, v[94:95]
	global_load_dword v126, v[4:5], off
	v_lshl_add_u64 v[4:5], v[2:3], 0, v[96:97]
	v_add_co_u32_e32 v6, vcc, s92, v4
	v_fma_f32 v26, v25, v26, v25
	s_nop 0
	v_addc_co_u32_e32 v7, vcc, 0, v5, vcc
	global_load_dword v155, v[4:5], off
	global_load_dword v157, v[6:7], off
	v_lshl_add_u64 v[4:5], v[0:1], 0, v[98:99]
	global_load_dword v124, v[4:5], off
	v_lshl_add_u64 v[4:5], v[2:3], 0, v[100:101]
	v_add_co_u32_e32 v6, vcc, s92, v4
	v_mul_f32_e32 v26, 0xbfcc422a, v26
	s_nop 0
	v_addc_co_u32_e32 v7, vcc, 0, v5, vcc
	global_load_dword v152, v[4:5], off
	global_load_dword v153, v[6:7], off
	v_lshl_add_u64 v[4:5], v[0:1], 0, v[102:103]
	global_load_dword v123, v[4:5], off
	v_lshl_add_u64 v[4:5], v[2:3], 0, v[104:105]
	v_add_co_u32_e32 v6, vcc, s92, v4
	v_lshl_add_u64 v[2:3], v[2:3], 0, v[110:111]
	s_nop 0
	v_addc_co_u32_e32 v7, vcc, 0, v5, vcc
	global_load_dword v158, v[4:5], off
	global_load_dword v159, v[6:7], off
	v_lshl_add_u64 v[4:5], v[0:1], 0, v[106:107]
	global_load_dword v121, v[4:5], off
	v_add_co_u32_e32 v4, vcc, s92, v2
	v_lshl_add_u64 v[0:1], v[0:1], 0, v[108:109]
	s_nop 0
	v_addc_co_u32_e32 v5, vcc, 0, v3, vcc
	global_load_dword v154, v[2:3], off
	global_load_dword v156, v[4:5], off
	ds_read_b64 v[2:3], v229 offset:63640
	global_load_dword v122, v[0:1], off
	v_add_u32_e32 v0, v120, v140
	v_ashrrev_i32_e32 v1, 31, v0
	v_mul_f32_e32 v26, 0x3fb8aa3b, v26
	s_waitcnt lgkmcnt(0)
	v_lshl_add_u64 v[0:1], v[0:1], 2, v[2:3]
	global_load_dword v125, v[0:1], off
	v_or_b32_e32 v0, v20, v139
	v_ashrrev_i32_e32 v1, 31, v0
	v_lshlrev_b64 v[0:1], 8, v[0:1]
	v_lshl_add_u64 v[0:1], v[72:73], 0, v[0:1]
	global_load_dwordx4 v[12:15], v[0:1], off
	global_load_dwordx4 v[8:11], v[0:1], off offset:64
	global_load_dwordx4 v[4:7], v[0:1], off offset:128
	s_nop 0
	global_load_dwordx4 v[0:3], v[0:1], off offset:192
	v_exp_f32_e32 v26, v26
	v_bfe_u32 v22, v21, 16, 1
	v_add3_u32 v21, v21, v22, s89
	ds_write_b16_d16_hi v28, v21 offset:35344
	v_add_f32_e32 v22, 1.0, v26
	v_rcp_f32_e32 v22, v22
	v_mul_f32_e32 v21, v24, v23
	v_bfe_u32 v23, v21, 16, 1
	v_add_f32_e32 v16, v164, v16
	v_add3_u32 v21, v21, v23, s89
	v_fmac_f32_e32 v16, v135, v143
	ds_write_b16_d16_hi v28, v21 offset:35872
	v_mul_f32_e32 v21, v25, v22
	v_mul_f32_e32 v22, 0x3d372713, v16
	v_mul_f32_e32 v22, v16, v22
	v_fma_f32 v22, v16, v22, v16
	v_mul_f32_e32 v22, 0xbfcc422a, v22
	v_mul_f32_e32 v22, 0x3fb8aa3b, v22
	v_exp_f32_e32 v22, v22
	v_bfe_u32 v23, v21, 16, 1
	v_add_f32_e32 v17, v161, v17
	v_add3_u32 v21, v21, v23, s89
	v_fmac_f32_e32 v17, v134, v143
	ds_write_b16_d16_hi v28, v21 offset:36400
	v_add_f32_e32 v21, 1.0, v22
	v_mul_f32_e32 v22, 0x3d372713, v17
	v_mul_f32_e32 v22, v17, v22
	v_fma_f32 v22, v17, v22, v17
	v_rcp_f32_e32 v21, v21
	v_mul_f32_e32 v22, 0xbfcc422a, v22
	v_mul_f32_e32 v22, 0x3fb8aa3b, v22
	v_exp_f32_e32 v22, v22
	v_mul_f32_e32 v16, v16, v21
	v_add_f32_e32 v18, v160, v18
	v_bfe_u32 v21, v16, 16, 1
	v_fmac_f32_e32 v18, v129, v143
	v_add3_u32 v16, v16, v21, s89
	v_add_f32_e32 v21, 1.0, v22
	v_mul_f32_e32 v22, 0x3d372713, v18
	v_mul_f32_e32 v22, v18, v22
	v_fma_f32 v22, v18, v22, v18
	v_mul_f32_e32 v22, 0xbfcc422a, v22
	v_mul_f32_e32 v22, 0x3fb8aa3b, v22
	v_rcp_f32_e32 v21, v21
	v_exp_f32_e32 v22, v22
	v_add_f32_e32 v19, v162, v19
	v_fmac_f32_e32 v19, v133, v143
	ds_write_b16_d16_hi v28, v16 offset:43264
	v_mul_f32_e32 v16, v17, v21
	v_add_f32_e32 v21, 1.0, v22
	v_mul_f32_e32 v22, 0x3d372713, v19
	v_mul_f32_e32 v22, v19, v22
	v_fma_f32 v22, v19, v22, v19
	v_mul_f32_e32 v22, 0xbfcc422a, v22
	v_mul_f32_e32 v22, 0x3fb8aa3b, v22
	v_exp_f32_e32 v22, v22
	v_rcp_f32_e32 v21, v21
	v_bfe_u32 v17, v16, 16, 1
	v_add3_u32 v16, v16, v17, s89
	v_add_f32_e32 v17, 1.0, v22
	v_rcp_f32_e32 v17, v17
	ds_write_b16_d16_hi v28, v16 offset:43792
	v_mul_f32_e32 v16, v18, v21
	v_bfe_u32 v18, v16, 16, 1
	v_add3_u32 v16, v16, v18, s89
	ds_write_b16_d16_hi v28, v16 offset:44320
	v_mul_f32_e32 v16, v19, v17
	v_bfe_u32 v17, v16, 16, 1
	v_add3_u32 v16, v16, v17, s89
	ds_write_b16_d16_hi v28, v16 offset:44848
	v_pk_mov_b32 v[16:17], v[116:117], v[116:117] op_sel:[1,0]
	v_mov_b32_e32 v18, v119

.LBB0_1485:
	v_pk_mul_f32 v[118:119], v[116:117], v[118:119] op_sel_hi:[1,0]
	v_add_u32_e32 v133, s0, v65
	v_pk_fma_f32 v[134:135], v[112:113], v[114:115], v[118:119] op_sel_hi:[1,0,1]
	v_pk_fma_f32 v[114:115], v[112:113], v[114:115], v[118:119] op_sel_hi:[1,0,1] neg_lo:[0,0,1] neg_hi:[0,0,1]
	v_cvt_pk_bf16_f32 v129, v114, v135
	v_pk_mul_f32 v[118:119], v[116:117], v[134:135] op_sel:[0,1]
	v_add_u32_e32 v143, 0x400, v133
	v_pk_fma_f32 v[134:135], v[112:113], v[114:115], v[118:119] op_sel_hi:[1,0,1]
	v_pk_fma_f32 v[114:115], v[112:113], v[114:115], v[118:119] op_sel_hi:[1,0,1] neg_lo:[0,0,1] neg_hi:[0,0,1]
	v_cvt_pk_bf16_f32 v118, v114, v135
	ds_write2_b32 v143, v118, v129 offset0:152 offset1:220
	v_pk_mul_f32 v[118:119], v[116:117], v[134:135] op_sel:[0,1]
	s_addk_i32 s0, 0xf780
	v_pk_fma_f32 v[134:135], v[112:113], v[114:115], v[118:119] op_sel_hi:[1,0,1]
	v_pk_fma_f32 v[114:115], v[112:113], v[114:115], v[118:119] op_sel_hi:[1,0,1] neg_lo:[0,0,1] neg_hi:[0,0,1]
	v_cvt_pk_bf16_f32 v129, v114, v135
	v_pk_mul_f32 v[118:119], v[116:117], v[134:135] op_sel:[0,1]
	s_cmpk_lg_i32 s0, 0xf780
	v_pk_fma_f32 v[134:135], v[112:113], v[114:115], v[118:119] op_sel_hi:[1,0,1]
	v_pk_fma_f32 v[114:115], v[112:113], v[114:115], v[118:119] op_sel_hi:[1,0,1] neg_lo:[0,0,1] neg_hi:[0,0,1]
	v_cvt_pk_bf16_f32 v118, v114, v135
	ds_write2_b32 v143, v118, v129 offset0:16 offset1:84
	v_pk_mul_f32 v[118:119], v[116:117], v[134:135] op_sel:[0,1]
	s_nop 0
	v_pk_fma_f32 v[134:135], v[112:113], v[114:115], v[118:119] op_sel_hi:[1,0,1]
	v_pk_fma_f32 v[114:115], v[112:113], v[114:115], v[118:119] op_sel_hi:[1,0,1] neg_lo:[0,0,1] neg_hi:[0,0,1]
	v_cvt_pk_bf16_f32 v129, v114, v135
	v_pk_mul_f32 v[118:119], v[116:117], v[134:135] op_sel:[0,1]
	s_nop 0
	v_pk_fma_f32 v[134:135], v[112:113], v[114:115], v[118:119] op_sel_hi:[1,0,1]
	v_pk_fma_f32 v[114:115], v[112:113], v[114:115], v[118:119] op_sel_hi:[1,0,1] neg_lo:[0,0,1] neg_hi:[0,0,1]
	v_cvt_pk_bf16_f32 v118, v114, v135
	ds_write2_b32 v133, v118, v129 offset0:136 offset1:204
	v_pk_mul_f32 v[118:119], v[116:117], v[134:135] op_sel:[0,1]
	s_nop 0
	v_pk_fma_f32 v[134:135], v[112:113], v[114:115], v[118:119] op_sel_hi:[1,0,1]
	v_pk_fma_f32 v[114:115], v[112:113], v[114:115], v[118:119] op_sel_hi:[1,0,1] neg_lo:[0,0,1] neg_hi:[0,0,1]
	v_bfe_u32 v119, v135, 16, 1
	v_bfe_u32 v118, v114, 16, 1
	v_add3_u32 v118, v114, v118, s89
	v_lshrrev_b32_e32 v118, 16, v118
	v_add3_u32 v119, v135, v119, s89
	v_pk_mul_f32 v[134:135], v[116:117], v[134:135] op_sel:[0,1]
	v_and_or_b32 v129, v119, s75, v118
	v_pk_fma_f32 v[118:119], v[112:113], v[114:115], v[134:135] op_sel_hi:[1,0,1]
	v_pk_fma_f32 v[114:115], v[112:113], v[114:115], v[134:135] op_sel_hi:[1,0,1] neg_lo:[0,0,1] neg_hi:[0,0,1]
	v_cvt_pk_bf16_f32 v115, v114, v119
	v_mov_b32_e32 v118, v119
	ds_write2_b32 v133, v115, v129 offset1:68
	s_cbranch_scc1 .LBB0_1485
	s_waitcnt vmcnt(7) lgkmcnt(11)
	v_mfma_f32_16x16x32_bf16 v[56:59], v[56:59], v[12:15], 0
	v_add_f32_e32 v129, v148, v149
	v_add_f32_e32 v143, v144, v145
	s_waitcnt vmcnt(6) lgkmcnt(10)
	v_mfma_f32_16x16x32_bf16 v[56:59], v[60:63], v[8:11], v[56:59]
	ds_read_b128 v[60:63], v131
	v_add_f32_e32 v134, v150, v151
	v_lshlrev_b32_e32 v120, 1, v120
	s_waitcnt vmcnt(5) lgkmcnt(8)
	v_mfma_f32_16x16x32_bf16 v[52:55], v[52:55], v[4:7], v[56:59]
	v_add_f32_e32 v144, v146, v147
	v_add_f32_e32 v133, v155, v157
	v_add_f32_e32 v145, v152, v153
	ds_read_b128 v[56:59], v131 offset:64
	s_waitcnt vmcnt(4) lgkmcnt(8)
	v_mfma_f32_16x16x32_bf16 v[48:51], v[48:51], v[0:3], v[52:55]
	v_add_f32_e32 v135, v158, v159
	v_add_f32_e32 v146, v154, v156
	s_mov_b32 s0, 0
	ds_read_b128 v[52:55], v131 offset:128
	s_waitcnt vmcnt(3) lgkmcnt(2)
	v_mfma_f32_16x16x32_bf16 v[48:51], v[60:63], v[28:31], v[48:51]
	ds_read_b128 v[60:63], v131 offset:192
	s_waitcnt vmcnt(2) lgkmcnt(2)
	v_mfma_f32_16x16x32_bf16 v[48:51], v[56:59], v[24:27], v[48:51]
	ds_read_b128 v[56:59], v131 offset:4352
	ds_read_b128 v[112:115], v131 offset:4416
	s_waitcnt vmcnt(1) lgkmcnt(3)
	v_mfma_f32_16x16x32_bf16 v[48:51], v[52:55], v[20:23], v[48:51]
	ds_read_b128 v[52:55], v131 offset:4480
	ds_read_b128 v[116:119], v131 offset:4544
	v_mfma_f32_16x16x32_bf16 v[12:15], v[44:47], v[12:15], 0
	s_waitcnt vmcnt(0) lgkmcnt(4)
	v_mfma_f32_16x16x32_bf16 v[48:51], v[60:63], v[16:19], v[48:51]
	v_mfma_f32_16x16x32_bf16 v[8:11], v[40:43], v[8:11], v[12:15]
	v_mfma_f32_16x16x32_bf16 v[4:7], v[36:39], v[4:7], v[8:11]
	s_nop 5
	v_add_f32_e32 v48, v129, v48
	v_fmac_f32_e32 v48, v128, v125
	v_mul_f32_e32 v60, 0x3d372713, v48
	v_mul_f32_e32 v44, v48, v60
	v_fma_f32 v44, v48, v44, v48
	v_mfma_f32_16x16x32_bf16 v[0:3], v[32:35], v[0:3], v[4:7]
	v_mul_f32_e32 v44, 0xbfcc422a, v44
	v_mul_f32_e32 v44, 0x3fb8aa3b, v44
	v_exp_f32_e32 v12, v44
	s_waitcnt lgkmcnt(3)
	v_mfma_f32_16x16x32_bf16 v[0:3], v[56:59], v[28:31], v[0:3]
	v_add_f32_e32 v49, v143, v49
	v_fmac_f32_e32 v49, v142, v125
	v_add_f32_e32 v8, 1.0, v12
	v_rcp_f32_e32 v8, v8
	s_waitcnt lgkmcnt(2)
	v_mfma_f32_16x16x32_bf16 v[0:3], v[112:115], v[24:27], v[0:3]
	v_mul_f32_e32 v61, 0x3d372713, v49
	v_add_f32_e32 v24, v134, v50
	v_mul_f32_e32 v5, v48, v8
	s_waitcnt lgkmcnt(1)
	v_mfma_f32_16x16x32_bf16 v[0:3], v[52:55], v[20:23], v[0:3]
	v_mul_f32_e32 v13, v49, v61
	v_bfe_u32 v6, v5, 16, 1
	v_fmac_f32_e32 v24, v127, v125
	v_fma_f32 v13, v49, v13, v49
	v_add3_u32 v5, v5, v6, s89
	v_mul_f32_e32 v6, 0x3d372713, v24
	v_mul_f32_e32 v9, 0xbfcc422a, v13
	v_mul_f32_e32 v6, v24, v6
	v_mul_f32_e32 v4, 0x3fb8aa3b, v9
	s_waitcnt lgkmcnt(0)
	v_mfma_f32_16x16x32_bf16 v[16:19], v[116:119], v[16:19], v[0:3]
	v_exp_f32_e32 v4, v4
	v_lshlrev_b32_e32 v112, 4, v141
	v_ashrrev_i32_e32 v113, 31, v112
	v_fma_f32 v0, v24, v6, v24
	v_mul_f32_e32 v0, 0xbfcc422a, v0
	v_mul_f32_e32 v0, 0x3fb8aa3b, v0
	v_exp_f32_e32 v0, v0
	v_add_f32_e32 v4, 1.0, v4
	v_rcp_f32_e32 v4, v4
	v_add3_u32 v28, v130, v120, v132
	v_add_f32_e32 v0, 1.0, v0
	v_rcp_f32_e32 v23, v0
	v_lshlrev_b64 v[0:1], 2, v[112:113]
	v_lshl_add_u64 v[2:3], v[76:77], 0, v[0:1]
	ds_write_b16_d16_hi v28, v5 offset:34816
	v_mul_f32_e32 v21, v49, v4
	v_lshl_add_u64 v[4:5], v[2:3], 0, v[80:81]
	v_lshl_add_u64 v[0:1], v[78:79], 0, v[0:1]
	v_add_co_u32_e32 v6, vcc, s92, v4
	v_add_u32_e32 v20, s6, v112
	s_nop 0
	v_addc_co_u32_e32 v7, vcc, 0, v5, vcc
	global_load_dword v114, v[4:5], off
	global_load_dword v115, v[6:7], off
	v_lshl_add_u64 v[4:5], v[0:1], 0, v[82:83]
	global_load_dword v113, v[4:5], off
	v_lshl_add_u64 v[4:5], v[2:3], 0, v[84:85]
	v_add_co_u32_e32 v6, vcc, s92, v4
	v_add_f32_e32 v25, v144, v51
	s_nop 0
	v_addc_co_u32_e32 v7, vcc, 0, v5, vcc
	global_load_dword v84, v[4:5], off
	global_load_dword v85, v[6:7], off
	v_lshl_add_u64 v[4:5], v[0:1], 0, v[86:87]
	global_load_dword v83, v[4:5], off
	v_lshl_add_u64 v[4:5], v[2:3], 0, v[88:89]
	v_add_co_u32_e32 v6, vcc, s92, v4
	v_fmac_f32_e32 v25, v126, v125
	s_nop 0
	v_addc_co_u32_e32 v7, vcc, 0, v5, vcc
	global_load_dword v86, v[4:5], off
	global_load_dword v87, v[6:7], off
	v_lshl_add_u64 v[4:5], v[0:1], 0, v[90:91]
	global_load_dword v82, v[4:5], off
	v_lshl_add_u64 v[4:5], v[2:3], 0, v[92:93]
	v_add_co_u32_e32 v6, vcc, s92, v4
	v_mul_f32_e32 v26, 0x3d372713, v25
	s_nop 0
	v_addc_co_u32_e32 v7, vcc, 0, v5, vcc
	global_load_dword v88, v[4:5], off
	global_load_dword v89, v[6:7], off
	v_lshl_add_u64 v[4:5], v[0:1], 0, v[94:95]
	global_load_dword v81, v[4:5], off
	v_lshl_add_u64 v[4:5], v[2:3], 0, v[96:97]
	v_add_co_u32_e32 v6, vcc, s92, v4
	v_mul_f32_e32 v26, v25, v26
	s_nop 0
	v_addc_co_u32_e32 v7, vcc, 0, v5, vcc
	global_load_dword v90, v[4:5], off
	global_load_dword v91, v[6:7], off
	v_lshl_add_u64 v[4:5], v[0:1], 0, v[98:99]
	global_load_dword v80, v[4:5], off
	v_lshl_add_u64 v[4:5], v[2:3], 0, v[100:101]
	v_add_co_u32_e32 v6, vcc, s92, v4
	v_fma_f32 v26, v25, v26, v25
	s_nop 0
	v_addc_co_u32_e32 v7, vcc, 0, v5, vcc
	global_load_dword v92, v[4:5], off
	global_load_dword v93, v[6:7], off
	v_lshl_add_u64 v[4:5], v[0:1], 0, v[102:103]
	global_load_dword v79, v[4:5], off
	v_lshl_add_u64 v[4:5], v[2:3], 0, v[104:105]
	v_add_co_u32_e32 v6, vcc, s92, v4
	v_lshl_add_u64 v[2:3], v[2:3], 0, v[110:111]
	s_nop 0
	v_addc_co_u32_e32 v7, vcc, 0, v5, vcc
	global_load_dword v94, v[4:5], off
	global_load_dword v95, v[6:7], off
	v_lshl_add_u64 v[4:5], v[0:1], 0, v[106:107]
	global_load_dword v78, v[4:5], off
	v_add_co_u32_e32 v4, vcc, s92, v2
	v_lshl_add_u64 v[0:1], v[0:1], 0, v[108:109]
	s_nop 0
	v_addc_co_u32_e32 v5, vcc, 0, v3, vcc
	global_load_dword v96, v[2:3], off
	global_load_dword v97, v[4:5], off
	ds_read_b64 v[2:3], v229 offset:63640
	global_load_dword v76, v[0:1], off
	v_add_u32_e32 v0, v112, v140
	v_ashrrev_i32_e32 v1, 31, v0
	v_mul_f32_e32 v26, 0xbfcc422a, v26
	s_waitcnt lgkmcnt(0)
	v_lshl_add_u64 v[0:1], v[0:1], 2, v[2:3]
	global_load_dword v77, v[0:1], off
	v_or_b32_e32 v0, v20, v139
	v_ashrrev_i32_e32 v1, 31, v0
	v_lshlrev_b64 v[0:1], 8, v[0:1]
	v_lshl_add_u64 v[0:1], v[72:73], 0, v[0:1]
	global_load_dwordx4 v[12:15], v[0:1], off
	global_load_dwordx4 v[8:11], v[0:1], off offset:64
	global_load_dwordx4 v[4:7], v[0:1], off offset:128
	s_nop 0
	global_load_dwordx4 v[0:3], v[0:1], off offset:192
	v_mul_f32_e32 v26, 0x3fb8aa3b, v26
	v_exp_f32_e32 v26, v26
	v_bfe_u32 v22, v21, 16, 1
	v_add3_u32 v21, v21, v22, s89
	ds_write_b16_d16_hi v28, v21 offset:35344
	v_add_f32_e32 v22, 1.0, v26
	v_rcp_f32_e32 v22, v22
	v_mul_f32_e32 v21, v24, v23
	v_bfe_u32 v23, v21, 16, 1
	v_add_f32_e32 v16, v133, v16
	v_add3_u32 v21, v21, v23, s89
	v_fmac_f32_e32 v16, v124, v125
	ds_write_b16_d16_hi v28, v21 offset:35872
	v_mul_f32_e32 v21, v25, v22
	v_mul_f32_e32 v22, 0x3d372713, v16
	v_mul_f32_e32 v22, v16, v22
	v_fma_f32 v22, v16, v22, v16
	v_mul_f32_e32 v22, 0xbfcc422a, v22
	v_mul_f32_e32 v22, 0x3fb8aa3b, v22
	v_exp_f32_e32 v22, v22
	v_bfe_u32 v23, v21, 16, 1
	v_add_f32_e32 v17, v145, v17
	v_add3_u32 v21, v21, v23, s89
	v_fmac_f32_e32 v17, v123, v125
	ds_write_b16_d16_hi v28, v21 offset:36400
	v_add_f32_e32 v21, 1.0, v22
	v_mul_f32_e32 v22, 0x3d372713, v17
	v_mul_f32_e32 v22, v17, v22
	v_fma_f32 v22, v17, v22, v17
	v_rcp_f32_e32 v21, v21
	v_mul_f32_e32 v22, 0xbfcc422a, v22
	v_mul_f32_e32 v22, 0x3fb8aa3b, v22
	v_exp_f32_e32 v22, v22
	v_mul_f32_e32 v16, v16, v21
	v_add_f32_e32 v18, v135, v18
	v_bfe_u32 v21, v16, 16, 1
	v_fmac_f32_e32 v18, v121, v125
	v_add3_u32 v16, v16, v21, s89
	v_add_f32_e32 v21, 1.0, v22
	v_mul_f32_e32 v22, 0x3d372713, v18
	v_mul_f32_e32 v22, v18, v22
	v_fma_f32 v22, v18, v22, v18
	v_mul_f32_e32 v22, 0xbfcc422a, v22
	v_mul_f32_e32 v22, 0x3fb8aa3b, v22
	v_rcp_f32_e32 v21, v21
	v_exp_f32_e32 v22, v22
	v_add_f32_e32 v19, v146, v19
	v_fmac_f32_e32 v19, v122, v125
	ds_write_b16_d16_hi v28, v16 offset:43264
	v_mul_f32_e32 v16, v17, v21
	v_add_f32_e32 v21, 1.0, v22
	v_mul_f32_e32 v22, 0x3d372713, v19
	v_mul_f32_e32 v22, v19, v22
	v_fma_f32 v22, v19, v22, v19
	v_mul_f32_e32 v22, 0xbfcc422a, v22
	v_mul_f32_e32 v22, 0x3fb8aa3b, v22
	v_exp_f32_e32 v22, v22
	v_rcp_f32_e32 v21, v21
	v_bfe_u32 v17, v16, 16, 1
	v_add3_u32 v16, v16, v17, s89
	v_add_f32_e32 v17, 1.0, v22
	v_rcp_f32_e32 v17, v17
	ds_write_b16_d16_hi v28, v16 offset:43792
	v_mul_f32_e32 v16, v18, v21
	v_bfe_u32 v18, v16, 16, 1
	v_add3_u32 v16, v16, v18, s89
	ds_write_b16_d16_hi v28, v16 offset:44320
	v_mul_f32_e32 v16, v19, v17
	v_bfe_u32 v17, v16, 16, 1
	v_add3_u32 v16, v16, v17, s89
	ds_write_b16_d16_hi v28, v16 offset:44848
	v_pk_mov_b32 v[16:17], v[70:71], v[70:71] op_sel:[1,0]
	v_mov_b32_e32 v18, v75

.LBB0_1489:
	v_pk_mul_f32 v[72:73], v[70:71], v[72:73] op_sel_hi:[1,0]
	v_add_u32_e32 v99, s0, v65
	v_pk_fma_f32 v[74:75], v[66:67], v[68:69], v[72:73] op_sel_hi:[1,0,1]
	v_pk_fma_f32 v[68:69], v[66:67], v[68:69], v[72:73] op_sel_hi:[1,0,1] neg_lo:[0,0,1] neg_hi:[0,0,1]
	v_cvt_pk_bf16_f32 v98, v68, v75
	v_pk_mul_f32 v[72:73], v[70:71], v[74:75] op_sel:[0,1]
	v_add_u32_e32 v100, 0x400, v99
	v_pk_fma_f32 v[74:75], v[66:67], v[68:69], v[72:73] op_sel_hi:[1,0,1]
	v_pk_fma_f32 v[68:69], v[66:67], v[68:69], v[72:73] op_sel_hi:[1,0,1] neg_lo:[0,0,1] neg_hi:[0,0,1]
	v_cvt_pk_bf16_f32 v72, v68, v75
	ds_write2_b32 v100, v72, v98 offset0:152 offset1:220
	v_pk_mul_f32 v[72:73], v[70:71], v[74:75] op_sel:[0,1]
	s_addk_i32 s0, 0xf780
	v_pk_fma_f32 v[74:75], v[66:67], v[68:69], v[72:73] op_sel_hi:[1,0,1]
	v_pk_fma_f32 v[68:69], v[66:67], v[68:69], v[72:73] op_sel_hi:[1,0,1] neg_lo:[0,0,1] neg_hi:[0,0,1]
	v_cvt_pk_bf16_f32 v98, v68, v75
	v_pk_mul_f32 v[72:73], v[70:71], v[74:75] op_sel:[0,1]
	s_cmpk_lg_i32 s0, 0xf780
	v_pk_fma_f32 v[74:75], v[66:67], v[68:69], v[72:73] op_sel_hi:[1,0,1]
	v_pk_fma_f32 v[68:69], v[66:67], v[68:69], v[72:73] op_sel_hi:[1,0,1] neg_lo:[0,0,1] neg_hi:[0,0,1]
	v_cvt_pk_bf16_f32 v72, v68, v75
	ds_write2_b32 v100, v72, v98 offset0:16 offset1:84
	v_pk_mul_f32 v[72:73], v[70:71], v[74:75] op_sel:[0,1]
	s_nop 0
	v_pk_fma_f32 v[74:75], v[66:67], v[68:69], v[72:73] op_sel_hi:[1,0,1]
	v_pk_fma_f32 v[68:69], v[66:67], v[68:69], v[72:73] op_sel_hi:[1,0,1] neg_lo:[0,0,1] neg_hi:[0,0,1]
	v_cvt_pk_bf16_f32 v98, v68, v75
	v_pk_mul_f32 v[72:73], v[70:71], v[74:75] op_sel:[0,1]
	s_nop 0
	v_pk_fma_f32 v[74:75], v[66:67], v[68:69], v[72:73] op_sel_hi:[1,0,1]
	v_pk_fma_f32 v[68:69], v[66:67], v[68:69], v[72:73] op_sel_hi:[1,0,1] neg_lo:[0,0,1] neg_hi:[0,0,1]
	v_cvt_pk_bf16_f32 v72, v68, v75
	ds_write2_b32 v99, v72, v98 offset0:136 offset1:204
	v_pk_mul_f32 v[72:73], v[70:71], v[74:75] op_sel:[0,1]
	s_nop 0
	v_pk_fma_f32 v[74:75], v[66:67], v[68:69], v[72:73] op_sel_hi:[1,0,1]
	v_pk_fma_f32 v[68:69], v[66:67], v[68:69], v[72:73] op_sel_hi:[1,0,1] neg_lo:[0,0,1] neg_hi:[0,0,1]
	v_bfe_u32 v73, v75, 16, 1
	v_bfe_u32 v72, v68, 16, 1
	v_add3_u32 v72, v68, v72, s89
	v_lshrrev_b32_e32 v72, 16, v72
	v_add3_u32 v73, v75, v73, s89
	v_pk_mul_f32 v[74:75], v[70:71], v[74:75] op_sel:[0,1]
	v_and_or_b32 v98, v73, s75, v72
	v_pk_fma_f32 v[72:73], v[66:67], v[68:69], v[74:75] op_sel_hi:[1,0,1]
	v_pk_fma_f32 v[68:69], v[66:67], v[68:69], v[74:75] op_sel_hi:[1,0,1] neg_lo:[0,0,1] neg_hi:[0,0,1]
	v_cvt_pk_bf16_f32 v69, v68, v73
	v_mov_b32_e32 v72, v73
	ds_write2_b32 v99, v69, v98 offset1:68
	s_cbranch_scc1 .LBB0_1489
	s_waitcnt vmcnt(7) lgkmcnt(11)
	v_mfma_f32_16x16x32_bf16 v[56:59], v[56:59], v[12:15], 0
	v_add_f32_e32 v65, v114, v115
	v_add_f32_e32 v69, v84, v85
	s_waitcnt lgkmcnt(9)
	v_mfma_f32_16x16x32_bf16 v[12:15], v[60:63], v[12:15], 0
	v_add_f32_e32 v67, v86, v87
	v_add_f32_e32 v70, v88, v89
	v_add_f32_e32 v66, v90, v91
	s_waitcnt vmcnt(6)
	v_mfma_f32_16x16x32_bf16 v[32:35], v[32:35], v[8:11], v[56:59]
	v_add_f32_e32 v71, v92, v93
	v_add_f32_e32 v68, v94, v95
	v_add_f32_e32 v72, v96, v97
	s_waitcnt lgkmcnt(8)
	v_mfma_f32_16x16x32_bf16 v[8:11], v[40:43], v[8:11], v[12:15]
	v_and_b32_e32 v40, 31, v137
	v_lshrrev_b32_e32 v41, 5, v138
	s_mov_b64 s[0:1], 0
	s_waitcnt vmcnt(5) lgkmcnt(7)
	v_mfma_f32_16x16x32_bf16 v[12:15], v[44:47], v[4:7], v[32:35]
	s_waitcnt lgkmcnt(5)
	v_mfma_f32_16x16x32_bf16 v[4:7], v[52:55], v[4:7], v[8:11]
	s_nop 0
	v_and_b32_e32 v34, 0xffffffdf, v137
	v_or_b32_e32 v32, 32, v137
	v_ashrrev_i32_e32 v35, 31, v34
	s_waitcnt vmcnt(4)
	v_mfma_f32_16x16x32_bf16 v[8:11], v[36:39], v[0:3], v[12:15]
	v_ashrrev_i32_e32 v33, 31, v32
	s_waitcnt lgkmcnt(4)
	v_mfma_f32_16x16x32_bf16 v[0:3], v[48:51], v[0:3], v[4:7]
	s_nop 2
	ds_read_b128 v[4:7], v131
	s_waitcnt vmcnt(3) lgkmcnt(0)
	v_mfma_f32_16x16x32_bf16 v[4:7], v[4:7], v[28:31], v[8:11]
	s_nop 2
	ds_read_b128 v[8:11], v131 offset:4352
	s_waitcnt lgkmcnt(0)
	v_mfma_f32_16x16x32_bf16 v[0:3], v[8:11], v[28:31], v[0:3]
	ds_read_b128 v[8:11], v131 offset:64
	s_waitcnt vmcnt(2) lgkmcnt(0)
	v_mfma_f32_16x16x32_bf16 v[4:7], v[8:11], v[24:27], v[4:7]
	ds_read_b128 v[8:11], v131 offset:4416
	s_waitcnt lgkmcnt(0)
	v_mfma_f32_16x16x32_bf16 v[0:3], v[8:11], v[24:27], v[0:3]
	ds_read_b128 v[8:11], v131 offset:128
	s_waitcnt vmcnt(1) lgkmcnt(0)
	v_mfma_f32_16x16x32_bf16 v[4:7], v[8:11], v[20:23], v[4:7]
	ds_read_b128 v[8:11], v131 offset:4480
	s_waitcnt lgkmcnt(0)
	v_mfma_f32_16x16x32_bf16 v[0:3], v[8:11], v[20:23], v[0:3]
	ds_read_b128 v[8:11], v131 offset:192
	s_waitcnt vmcnt(0) lgkmcnt(0)
	v_mfma_f32_16x16x32_bf16 v[4:7], v[8:11], v[16:19], v[4:7]
	ds_read_b128 v[8:11], v131 offset:4544
	s_nop 6
	v_add_f32_e32 v4, v65, v4
	v_fmac_f32_e32 v4, v113, v77
	s_waitcnt lgkmcnt(0)
	v_mfma_f32_16x16x32_bf16 v[0:3], v[8:11], v[16:19], v[0:3]
	v_mul_f32_e32 v9, 0x3d372713, v4
	v_mul_f32_e32 v9, v4, v9
	v_fma_f32 v9, v4, v9, v4
	v_mul_f32_e32 v9, 0xbfcc422a, v9
	v_mul_f32_e32 v9, 0x3fb8aa3b, v9
	v_exp_f32_e32 v9, v9
	v_lshlrev_b32_e32 v8, 1, v112
	v_add3_u32 v8, v130, v8, v132
	v_add_f32_e32 v0, v66, v0
	v_add_f32_e32 v9, 1.0, v9
	v_rcp_f32_e32 v9, v9
	v_fmac_f32_e32 v0, v80, v77
	v_mul_f32_e32 v4, v4, v9
	v_bfe_u32 v9, v4, 16, 1
	v_add3_u32 v4, v4, v9, s89
	ds_write_b16_d16_hi v8, v4 offset:34816
	v_add_f32_e32 v4, v69, v5
	v_fmac_f32_e32 v4, v83, v77
	v_mul_f32_e32 v5, 0x3d372713, v4
	v_mul_f32_e32 v5, v4, v5
	v_fma_f32 v5, v4, v5, v4
	v_mul_f32_e32 v5, 0xbfcc422a, v5
	v_mul_f32_e32 v5, 0x3fb8aa3b, v5
	v_exp_f32_e32 v5, v5
	s_nop 0
	v_add_f32_e32 v5, 1.0, v5
	v_rcp_f32_e32 v5, v5
	s_nop 0
	v_mul_f32_e32 v4, v4, v5
	v_bfe_u32 v5, v4, 16, 1
	v_add3_u32 v4, v4, v5, s89
	ds_write_b16_d16_hi v8, v4 offset:35344
	v_add_f32_e32 v4, v67, v6
	v_fmac_f32_e32 v4, v82, v77
	v_mul_f32_e32 v5, 0x3d372713, v4
	v_mul_f32_e32 v5, v4, v5
	v_fma_f32 v5, v4, v5, v4
	v_mul_f32_e32 v5, 0xbfcc422a, v5
	v_mul_f32_e32 v5, 0x3fb8aa3b, v5
	v_exp_f32_e32 v5, v5
	v_mul_u32_u24_e32 v6, 0x210, v40
	v_add_f32_e32 v5, 1.0, v5
	v_rcp_f32_e32 v5, v5
	s_nop 0
	v_mul_f32_e32 v4, v4, v5
	v_bfe_u32 v5, v4, 16, 1
	v_add3_u32 v4, v4, v5, s89
	ds_write_b16_d16_hi v8, v4 offset:35872
	v_add_f32_e32 v4, v70, v7
	v_fmac_f32_e32 v4, v81, v77
	v_mul_f32_e32 v5, 0x3d372713, v4
	v_mul_f32_e32 v5, v4, v5
	v_fma_f32 v5, v4, v5, v4
	v_mul_f32_e32 v5, 0xbfcc422a, v5
	v_mul_f32_e32 v5, 0x3fb8aa3b, v5
	v_exp_f32_e32 v5, v5
	v_lshlrev_b32_e32 v7, 4, v41
	v_add3_u32 v42, v6, v7, s26
	v_lshrrev_b32_e32 v6, 1, v137
	v_add_f32_e32 v5, 1.0, v5
	v_rcp_f32_e32 v5, v5
	v_and_b32_e32 v6, 16, v6
	v_mul_f32_e32 v4, v4, v5
	v_bfe_u32 v5, v4, 16, 1
	v_add3_u32 v4, v4, v5, s89
	ds_write_b16_d16_hi v8, v4 offset:36400
	v_mul_f32_e32 v4, 0x3d372713, v0
	v_mul_f32_e32 v4, v0, v4
	v_fma_f32 v4, v0, v4, v0
	v_mul_f32_e32 v4, 0xbfcc422a, v4
	v_mul_f32_e32 v4, 0x3fb8aa3b, v4
	v_exp_f32_e32 v4, v4
	s_nop 0
	v_add_f32_e32 v4, 1.0, v4
	v_rcp_f32_e32 v4, v4
	s_nop 0
	v_mul_f32_e32 v0, v0, v4
	v_bfe_u32 v4, v0, 16, 1
	v_add3_u32 v0, v0, v4, s89
	ds_write_b16_d16_hi v8, v0 offset:43264
	v_add_f32_e32 v0, v71, v1
	v_fmac_f32_e32 v0, v79, v77
	v_mul_f32_e32 v1, 0x3d372713, v0
	v_mul_f32_e32 v1, v0, v1
	v_fma_f32 v1, v0, v1, v0
	v_mul_f32_e32 v1, 0xbfcc422a, v1
	v_mul_f32_e32 v1, 0x3fb8aa3b, v1
	v_exp_f32_e32 v1, v1
	v_lshlrev_b64 v[4:5], 9, v[32:33]
	v_or_b32_e32 v4, v4, v6
	v_add_f32_e32 v1, 1.0, v1
	v_rcp_f32_e32 v1, v1
	s_nop 0
	v_mul_f32_e32 v0, v0, v1
	v_bfe_u32 v1, v0, 16, 1
	v_add3_u32 v0, v0, v1, s89
	ds_write_b16_d16_hi v8, v0 offset:43792
	v_add_f32_e32 v0, v68, v2
	v_fmac_f32_e32 v0, v78, v77
	v_mul_f32_e32 v1, 0x3d372713, v0
	v_mul_f32_e32 v1, v0, v1
	v_fma_f32 v1, v0, v1, v0
	v_mul_f32_e32 v1, 0xbfcc422a, v1
	v_mul_f32_e32 v1, 0x3fb8aa3b, v1
	v_exp_f32_e32 v1, v1
	s_nop 0
	v_add_f32_e32 v1, 1.0, v1
	v_rcp_f32_e32 v1, v1
	s_nop 0
	v_mul_f32_e32 v0, v0, v1
	v_bfe_u32 v1, v0, 16, 1
	v_add3_u32 v0, v0, v1, s89
	ds_write_b16_d16_hi v8, v0 offset:44320
	v_add_f32_e32 v0, v72, v3
	v_fmac_f32_e32 v0, v76, v77
	v_mul_f32_e32 v1, 0x3d372713, v0
	v_mul_f32_e32 v1, v0, v1
	v_fma_f32 v1, v0, v1, v0
	v_mul_f32_e32 v1, 0xbfcc422a, v1
	v_mul_f32_e32 v1, 0x3fb8aa3b, v1
	v_exp_f32_e32 v1, v1
	v_lshlrev_b64 v[2:3], 9, v[34:35]
	v_or_b32_e32 v2, v2, v6
	v_add_f32_e32 v1, 1.0, v1
	v_rcp_f32_e32 v1, v1
	s_nop 0
	v_mul_f32_e32 v0, v0, v1
	v_bfe_u32 v1, v0, 16, 1
	v_add3_u32 v0, v0, v1, s89
	ds_write_b16_d16_hi v8, v0 offset:44848
	s_waitcnt lgkmcnt(0)
	s_barrier
	ds_read_b64 v[0:1], v229 offset:63760
	s_waitcnt lgkmcnt(0)
	v_lshl_add_u64 v[36:37], v[0:1], 0, v[4:5]
	v_lshl_add_u64 v[38:39], v[0:1], 0, v[2:3]
	v_mov_b32_e32 v0, 0
	v_mov_b32_e32 v1, v0
	v_mov_b32_e32 v2, v0
	v_mov_b32_e32 v3, v0
	v_mov_b32_e32 v4, v0
	v_mov_b32_e32 v5, v0
	v_mov_b32_e32 v6, v0
	v_mov_b32_e32 v7, v0
	v_mov_b32_e32 v8, v0
	v_mov_b32_e32 v9, v0
	v_mov_b32_e32 v10, v0
	v_mov_b32_e32 v11, v0
	v_mov_b32_e32 v12, v0
	v_mov_b32_e32 v13, v0
	v_mov_b32_e32 v14, v0
	v_mov_b32_e32 v15, v0
	v_mov_b32_e32 v16, v0
	v_mov_b32_e32 v17, v0
	v_mov_b32_e32 v18, v0
	v_mov_b32_e32 v19, v0
	v_mov_b32_e32 v20, v0
	v_mov_b32_e32 v21, v0
	v_mov_b32_e32 v22, v0
	v_mov_b32_e32 v23, v0
	v_mov_b32_e32 v24, v0
	v_mov_b32_e32 v25, v0
	v_mov_b32_e32 v26, v0
	v_mov_b32_e32 v27, v0
	v_mov_b32_e32 v28, v0
	v_mov_b32_e32 v29, v0
	v_mov_b32_e32 v30, v0
	v_mov_b32_e32 v31, v0
